# topk: half-cleaner max fused into the sorter's last max (v_max3) in the six merge blocks, and the never-taken overflow clamp of the softmax exp (argument <= 0) dropped; on top of v062
# speedup vs baseline: 1.0077x; 1.0023x over previous
.LBB0_22:
	v_or_b32_e32 v2, s44, v118
	v_mov_b32_e32 v3, v1
	v_lshlrev_b64 v[46:47], 7, v[2:3]
	v_lshl_add_u64 v[2:3], v[62:63], 0, v[46:47]
	global_load_dwordx4 v[30:33], v[2:3], off
	global_load_dwordx4 v[26:29], v[2:3], off offset:32
	global_load_dwordx4 v[22:25], v[2:3], off offset:64
	global_load_dwordx4 v[18:21], v[2:3], off offset:96
	s_nop 0
	global_load_dwordx4 v[2:5], v[66:67], off
	global_load_dwordx4 v[34:37], v[66:67], off offset:32
	global_load_dwordx4 v[38:41], v[66:67], off offset:64
	global_load_dwordx4 v[42:45], v[66:67], off offset:96
	s_waitcnt vmcnt(0)
	v_mfma_f32_32x32x16_bf16 v[2:17], v[2:5], v[30:33], 0
	s_waitcnt vmcnt(2)
	v_mfma_f32_32x32x16_bf16 v[2:17], v[34:37], v[26:29], v[2:17]
	s_waitcnt vmcnt(1)
	v_mfma_f32_32x32x16_bf16 v[2:17], v[38:41], v[22:25], v[2:17]
	s_waitcnt vmcnt(0)
	v_mfma_f32_32x32x16_bf16 v[2:17], v[42:45], v[18:21], v[2:17]
	s_nop 11
	v_and_or_b32 v2, v2, s33, v120
	v_and_or_b32 v3, v3, s33, v122
	v_and_or_b32 v4, v4, s33, v123
	v_and_or_b32 v5, v5, s33, v124
	v_and_or_b32 v6, v6, s33, v125
	v_and_or_b32 v7, v7, s33, v126
	v_and_or_b32 v8, v8, s33, v127
	v_and_or_b32 v9, v9, s33, v128
	v_and_or_b32 v10, v10, s33, v129
	v_and_or_b32 v11, v11, s33, v136
	v_and_or_b32 v12, v12, s33, v137
	v_and_or_b32 v13, v13, s33, v138
	v_and_or_b32 v14, v14, s33, v139
	v_and_or_b32 v15, v15, s33, v140
	v_and_or_b32 v16, v16, s33, v141
	v_and_or_b32 v17, v17, s33, v142
	global_load_dwordx4 v[34:37], v[68:69], off offset:96
	global_load_dwordx4 v[38:41], v[68:69], off offset:64
	global_load_dwordx4 v[42:45], v[68:69], off offset:32
	global_load_dwordx4 v[232:235], v[68:69], off
	v_max_f32_e32 v206, v2, v15
	v_min_f32_e32 v15, v2, v15
	v_max_f32_e32 v207, v3, v14
	v_min_f32_e32 v14, v3, v14
	v_max_f32_e32 v227, v4, v17
	v_min_f32_e32 v17, v4, v17
	v_max_f32_e32 v228, v5, v16
	v_min_f32_e32 v16, v5, v16
	v_max_f32_e32 v229, v6, v10
	v_min_f32_e32 v10, v6, v10
	v_max_f32_e32 v230, v7, v8
	v_min_f32_e32 v8, v7, v8
	v_max_f32_e32 v231, v9, v13
	v_min_f32_e32 v13, v9, v13
	v_max_f32_e32 v2, v11, v12
	v_min_f32_e32 v12, v11, v12
	v_max_f32_e32 v3, v206, v230
	v_min_f32_e32 v230, v206, v230
	v_max_f32_e32 v206, v207, v231
	v_min_f32_e32 v231, v207, v231
	v_max_f32_e32 v207, v227, v2
	v_min_f32_e32 v2, v227, v2
	v_max_f32_e32 v227, v228, v229
	v_min_f32_e32 v229, v228, v229
	v_max_f32_e32 v228, v8, v15
	v_min_f32_e32 v15, v8, v15
	v_max_f32_e32 v4, v10, v16
	v_min_f32_e32 v16, v10, v16
	v_max_f32_e32 v5, v12, v17
	v_min_f32_e32 v17, v12, v17
	v_max_f32_e32 v6, v13, v14
	v_min_f32_e32 v14, v13, v14
	v_max_f32_e32 v7, v3, v206
	v_min_f32_e32 v206, v3, v206
	v_max_f32_e32 v3, v207, v227
	v_min_f32_e32 v227, v207, v227
	v_max_f32_e32 v207, v229, v230
	v_min_f32_e32 v230, v229, v230
	v_max_f32_e32 v229, v228, v4
	v_min_f32_e32 v4, v228, v4
	v_max_f32_e32 v228, v231, v2
	v_min_f32_e32 v2, v231, v2
	v_max_f32_e32 v231, v5, v6
	v_min_f32_e32 v6, v5, v6
	v_max_f32_e32 v5, v14, v15
	v_min_f32_e32 v15, v14, v15
	v_max_f32_e32 v8, v16, v17
	v_min_f32_e32 v17, v16, v17
	v_max_f32_e32 v48, v7, v3
	v_min_f32_e32 v3, v7, v3
	v_max_f32_e32 v7, v206, v227
	v_min_f32_e32 v227, v206, v227
	v_max_f32_e32 v206, v207, v231
	v_min_f32_e32 v231, v207, v231
	v_max_f32_e32 v207, v230, v6
	v_min_f32_e32 v6, v230, v6
	v_max_f32_e32 v230, v229, v228
	v_min_f32_e32 v228, v229, v228
	v_max_f32_e32 v229, v4, v2
	v_min_f32_e32 v2, v4, v2
	v_max_f32_e32 v4, v5, v8
	v_min_f32_e32 v8, v5, v8
	v_min_f32_e32 v205, v15, v17
	v_max_f32_e32 v15, v15, v17
	v_max_f32_e32 v5, v7, v3
	v_min_f32_e32 v3, v7, v3
	v_max_f32_e32 v7, v227, v4
	v_min_f32_e32 v4, v227, v4
	v_max_f32_e32 v227, v206, v230
	v_min_f32_e32 v230, v206, v230
	v_max_f32_e32 v206, v207, v228
	v_min_f32_e32 v228, v207, v228
	v_max_f32_e32 v207, v229, v231
	v_min_f32_e32 v231, v229, v231
	v_max_f32_e32 v229, v2, v6
	v_min_f32_e32 v6, v2, v6
	v_max_f32_e32 v2, v15, v8
	v_min_f32_e32 v8, v15, v8
	v_max_f32_e32 v49, v5, v227
	v_min_f32_e32 v227, v5, v227
	v_max_f32_e32 v5, v3, v230
	v_min_f32_e32 v230, v3, v230
	v_max_f32_e32 v3, v206, v207
	v_min_f32_e32 v207, v206, v207
	v_max_f32_e32 v206, v228, v231
	v_min_f32_e32 v231, v228, v231
	v_max_f32_e32 v228, v229, v2
	v_min_f32_e32 v2, v229, v2
	v_min_f32_e32 v154, v6, v8
	v_max_f32_e32 v6, v6, v8
	v_max_f32_e32 v50, v5, v227
	v_min_f32_e32 v227, v5, v227
	v_max_f32_e32 v229, v7, v230
	v_min_f32_e32 v230, v7, v230
	v_max_f32_e32 v5, v228, v4
	v_min_f32_e32 v4, v228, v4
	v_min_f32_e32 v61, v6, v2
	v_max_f32_e32 v6, v6, v2
	v_max_f32_e32 v228, v229, v3
	v_min_f32_e32 v3, v229, v3
	v_max_f32_e32 v229, v230, v207
	v_min_f32_e32 v207, v230, v207
	v_max_f32_e32 v230, v206, v5
	v_min_f32_e32 v5, v206, v5
	v_max_f32_e32 v206, v231, v4
	v_min_f32_e32 v4, v231, v4
	v_max_f32_e32 v51, v228, v227
	v_min_f32_e32 v52, v228, v227
	v_max_f32_e32 v53, v3, v229
	v_min_f32_e32 v229, v3, v229
	v_max_f32_e32 v227, v230, v207
	v_min_f32_e32 v207, v230, v207
	v_min_f32_e32 v58, v5, v206
	v_max_f32_e32 v5, v5, v206
	v_max_f32_e32 v59, v6, v4
	v_min_f32_e32 v60, v6, v4
	v_max_f32_e32 v54, v229, v227
	v_min_f32_e32 v55, v229, v227
	v_max_f32_e32 v56, v207, v5
	v_min_f32_e32 v57, v207, v5
	s_waitcnt vmcnt(0)
	v_mfma_f32_32x32x16_bf16 v[2:17], v[232:235], v[30:33], 0
	v_mfma_f32_32x32x16_bf16 v[2:17], v[42:45], v[26:29], v[2:17]
	v_mfma_f32_32x32x16_bf16 v[2:17], v[38:41], v[22:25], v[2:17]
	v_mfma_f32_32x32x16_bf16 v[2:17], v[34:37], v[18:21], v[2:17]
	s_nop 11
	v_and_or_b32 v2, v2, s33, v143
	v_and_or_b32 v3, v3, s33, v144
	v_and_or_b32 v4, v4, s33, v145
	v_and_or_b32 v5, v5, s33, v146
	v_and_or_b32 v6, v6, s33, v147
	v_and_or_b32 v7, v7, s33, v148
	v_and_or_b32 v8, v8, s33, v149
	v_and_or_b32 v9, v9, s33, v150
	v_and_or_b32 v10, v10, s33, v151
	v_and_or_b32 v11, v11, s33, v152
	v_and_or_b32 v12, v12, s33, v153
	v_and_or_b32 v13, v13, s33, v160
	v_and_or_b32 v14, v14, s33, v161
	v_and_or_b32 v15, v15, s33, v162
	v_and_or_b32 v16, v16, s33, v163
	v_and_or_b32 v17, v17, s33, v164
	global_load_dwordx4 v[34:37], v[70:71], off offset:96
	global_load_dwordx4 v[38:41], v[70:71], off offset:64
	global_load_dwordx4 v[42:45], v[70:71], off offset:32
	global_load_dwordx4 v[232:235], v[70:71], off
	v_max_f32_e32 v206, v2, v15
	v_min_f32_e32 v15, v2, v15
	v_max_f32_e32 v2, v3, v14
	v_min_f32_e32 v14, v3, v14
	v_max_f32_e32 v3, v4, v17
	v_min_f32_e32 v17, v4, v17
	v_max_f32_e32 v4, v5, v16
	v_min_f32_e32 v16, v5, v16
	v_max_f32_e32 v5, v6, v10
	v_min_f32_e32 v10, v6, v10
	v_max_f32_e32 v6, v7, v8
	v_min_f32_e32 v8, v7, v8
	v_max_f32_e32 v7, v9, v13
	v_min_f32_e32 v13, v9, v13
	v_max_f32_e32 v9, v11, v12
	v_min_f32_e32 v12, v11, v12
	v_max_f32_e32 v11, v206, v6
	v_min_f32_e32 v6, v206, v6
	v_max_f32_e32 v206, v2, v7
	v_min_f32_e32 v7, v2, v7
	v_max_f32_e32 v2, v3, v9
	v_min_f32_e32 v9, v3, v9
	v_max_f32_e32 v3, v4, v5
	v_min_f32_e32 v5, v4, v5
	v_max_f32_e32 v4, v8, v15
	v_min_f32_e32 v15, v8, v15
	v_max_f32_e32 v8, v10, v16
	v_min_f32_e32 v16, v10, v16
	v_max_f32_e32 v10, v12, v17
	v_min_f32_e32 v17, v12, v17
	v_max_f32_e32 v12, v13, v14
	v_min_f32_e32 v14, v13, v14
	v_max_f32_e32 v13, v11, v206
	v_min_f32_e32 v206, v11, v206
	v_max_f32_e32 v11, v2, v3
	v_min_f32_e32 v3, v2, v3
	v_max_f32_e32 v2, v5, v6
	v_min_f32_e32 v6, v5, v6
	v_max_f32_e32 v5, v4, v8
	v_min_f32_e32 v8, v4, v8
	v_max_f32_e32 v4, v7, v9
	v_min_f32_e32 v9, v7, v9
	v_max_f32_e32 v7, v10, v12
	v_min_f32_e32 v12, v10, v12
	v_max_f32_e32 v10, v14, v15
	v_min_f32_e32 v15, v14, v15
	v_max_f32_e32 v14, v16, v17
	v_min_f32_e32 v17, v16, v17
	v_max3_f32 v16, v13, v11, v205
	v_min_f32_e32 v11, v13, v11
	v_max_f32_e32 v13, v206, v3
	v_min_f32_e32 v3, v206, v3
	v_max_f32_e32 v205, v2, v7
	v_min_f32_e32 v7, v2, v7
	v_max_f32_e32 v2, v6, v12
	v_min_f32_e32 v12, v6, v12
	v_max_f32_e32 v6, v5, v4
	v_min_f32_e32 v4, v5, v4
	v_max_f32_e32 v5, v8, v9
	v_min_f32_e32 v9, v8, v9
	v_max_f32_e32 v8, v10, v14
	v_min_f32_e32 v14, v10, v14
	v_max_f32_e32 v10, v15, v17
	v_min_f32_e32 v17, v15, v17
	v_max_f32_e32 v15, v13, v11
	v_min_f32_e32 v11, v13, v11
	v_max_f32_e32 v13, v3, v8
	v_min_f32_e32 v8, v3, v8
	v_max_f32_e32 v3, v205, v6
	v_min_f32_e32 v6, v205, v6
	v_max_f32_e32 v205, v2, v4
	v_min_f32_e32 v4, v2, v4
	v_max_f32_e32 v2, v5, v7
	v_min_f32_e32 v7, v5, v7
	v_max_f32_e32 v5, v9, v12
	v_min_f32_e32 v12, v9, v12
	v_max_f32_e32 v9, v10, v14
	v_min_f32_e32 v14, v10, v14
	v_max3_f32 v10, v15, v3, v154
	v_min_f32_e32 v3, v15, v3
	v_max_f32_e32 v15, v11, v6
	v_min_f32_e32 v6, v11, v6
	v_max_f32_e32 v11, v205, v2
	v_min_f32_e32 v2, v205, v2
	v_max_f32_e32 v154, v4, v7
	v_min_f32_e32 v7, v4, v7
	v_max_f32_e32 v4, v5, v9
	v_min_f32_e32 v9, v5, v9
	v_max_f32_e32 v5, v12, v14
	v_min_f32_e32 v14, v12, v14
	v_max3_f32 v12, v15, v3, v61
	v_min_f32_e32 v3, v15, v3
	v_max_f32_e32 v15, v13, v6
	v_min_f32_e32 v6, v13, v6
	v_max_f32_e32 v13, v4, v8
	v_min_f32_e32 v8, v4, v8
	v_max_f32_e32 v4, v5, v9
	v_min_f32_e32 v9, v5, v9
	v_max_f32_e32 v5, v15, v11
	v_min_f32_e32 v11, v15, v11
	v_max_f32_e32 v15, v6, v2
	v_min_f32_e32 v2, v6, v2
	v_max_f32_e32 v6, v154, v13
	v_min_f32_e32 v13, v154, v13
	v_max_f32_e32 v61, v7, v8
	v_min_f32_e32 v8, v7, v8
	v_max3_f32 v7, v5, v3, v60
	v_min_f32_e32 v3, v5, v3
	v_max3_f32 v5, v11, v15, v58
	v_min_f32_e32 v15, v11, v15
	v_max_f32_e32 v11, v6, v2
	v_min_f32_e32 v2, v6, v2
	v_max_f32_e32 v6, v13, v61
	v_min_f32_e32 v61, v13, v61
	v_max3_f32 v13, v4, v8, v52
	v_min_f32_e32 v8, v4, v8
	v_max3_f32 v4, v15, v11, v57
	v_min_f32_e32 v11, v15, v11
	v_max3_f32 v15, v2, v6, v55
	v_min_f32_e32 v6, v2, v6
	v_max_f32_e32 v17, v48, v17
	v_max_f32_e32 v14, v49, v14
	v_max_f32_e32 v9, v50, v9
	v_max_f32_e32 v8, v51, v8
	v_max_f32_e32 v61, v53, v61
	v_max_f32_e32 v6, v54, v6
	v_max_f32_e32 v11, v56, v11
	v_max_f32_e32 v3, v59, v3
	v_max_f32_e32 v2, v16, v15
	v_min_f32_e32 v15, v16, v15
	v_max_f32_e32 v16, v10, v6
	v_min_f32_e32 v6, v10, v6
	v_max_f32_e32 v10, v12, v61
	v_min_f32_e32 v61, v12, v61
	v_max_f32_e32 v12, v7, v13
	v_min_f32_e32 v13, v7, v13
	v_max_f32_e32 v7, v3, v8
	v_min_f32_e32 v8, v3, v8
	v_max_f32_e32 v3, v5, v9
	v_min_f32_e32 v9, v5, v9
	v_max_f32_e32 v5, v4, v14
	v_min_f32_e32 v14, v4, v14
	v_max_f32_e32 v4, v11, v17
	v_min_f32_e32 v17, v11, v17
	v_max_f32_e32 v11, v2, v7
	v_min_f32_e32 v7, v2, v7
	v_max_f32_e32 v2, v16, v3
	v_min_f32_e32 v3, v16, v3
	v_max_f32_e32 v16, v10, v5
	v_min_f32_e32 v5, v10, v5
	v_max_f32_e32 v10, v12, v4
	v_min_f32_e32 v4, v12, v4
	v_max_f32_e32 v12, v15, v8
	v_min_f32_e32 v8, v15, v8
	v_max_f32_e32 v15, v6, v9
	v_min_f32_e32 v9, v6, v9
	v_max_f32_e32 v6, v61, v14
	v_min_f32_e32 v14, v61, v14
	v_max_f32_e32 v48, v13, v17
	v_min_f32_e32 v17, v13, v17
	v_max_f32_e32 v13, v11, v16
	v_min_f32_e32 v16, v11, v16
	v_max_f32_e32 v11, v2, v10
	v_min_f32_e32 v10, v2, v10
	v_max_f32_e32 v2, v7, v5
	v_min_f32_e32 v5, v7, v5
	v_max_f32_e32 v7, v3, v4
	v_min_f32_e32 v4, v3, v4
	v_max_f32_e32 v3, v12, v6
	v_min_f32_e32 v6, v12, v6
	v_max_f32_e32 v12, v15, v48
	v_min_f32_e32 v48, v15, v48
	v_max_f32_e32 v15, v8, v14
	v_min_f32_e32 v14, v8, v14
	v_max_f32_e32 v8, v9, v17
	v_min_f32_e32 v17, v9, v17
	v_max_f32_e32 v206, v13, v11
	v_min_f32_e32 v207, v13, v11
	v_max_f32_e32 v227, v16, v10
	v_min_f32_e32 v228, v16, v10
	v_max_f32_e32 v229, v2, v7
	v_min_f32_e32 v230, v2, v7
	v_max_f32_e32 v231, v5, v4
	v_min_f32_e32 v4, v5, v4
	v_max_f32_e32 v49, v3, v12
	v_min_f32_e32 v50, v3, v12
	v_max_f32_e32 v51, v6, v48
	v_min_f32_e32 v52, v6, v48
	v_max_f32_e32 v53, v15, v8
	v_min_f32_e32 v54, v15, v8
	v_max_f32_e32 v55, v14, v17
	v_min_f32_e32 v56, v14, v17
	v_mov_b32_e32 v48, v4
	s_waitcnt vmcnt(0)
	v_mfma_f32_32x32x16_bf16 v[2:17], v[232:235], v[30:33], 0
	v_mfma_f32_32x32x16_bf16 v[2:17], v[42:45], v[26:29], v[2:17]
	v_mfma_f32_32x32x16_bf16 v[2:17], v[38:41], v[22:25], v[2:17]
	v_mfma_f32_32x32x16_bf16 v[2:17], v[34:37], v[18:21], v[2:17]
	s_nop 11
	v_and_or_b32 v2, v2, s33, v165
	v_and_or_b32 v3, v3, s33, v166
	v_and_or_b32 v4, v4, s33, v167
	v_and_or_b32 v5, v5, s33, v168
	v_and_or_b32 v6, v6, s33, v169
	v_and_or_b32 v7, v7, s33, v170
	v_and_or_b32 v8, v8, s33, v171
	v_and_or_b32 v9, v9, s33, v172
	v_and_or_b32 v10, v10, s33, v173
	v_and_or_b32 v11, v11, s33, v174
	v_and_or_b32 v12, v12, s33, v175
	v_and_or_b32 v13, v13, s33, v184
	v_and_or_b32 v14, v14, s33, v185
	v_and_or_b32 v15, v15, s33, v186
	v_and_or_b32 v16, v16, s33, v187
	v_and_or_b32 v17, v17, s33, v188
	global_load_dwordx4 v[34:37], v[72:73], off offset:96
	global_load_dwordx4 v[38:41], v[72:73], off offset:64
	global_load_dwordx4 v[42:45], v[72:73], off offset:32
	global_load_dwordx4 v[232:235], v[72:73], off
	v_max_f32_e32 v57, v2, v15
	v_min_f32_e32 v15, v2, v15
	v_max_f32_e32 v2, v3, v14
	v_min_f32_e32 v14, v3, v14
	v_max_f32_e32 v3, v4, v17
	v_min_f32_e32 v17, v4, v17
	v_max_f32_e32 v4, v5, v16
	v_min_f32_e32 v16, v5, v16
	v_max_f32_e32 v5, v6, v10
	v_min_f32_e32 v10, v6, v10
	v_max_f32_e32 v6, v7, v8
	v_min_f32_e32 v8, v7, v8
	v_max_f32_e32 v7, v9, v13
	v_min_f32_e32 v13, v9, v13
	v_max_f32_e32 v9, v11, v12
	v_min_f32_e32 v12, v11, v12
	v_max_f32_e32 v11, v57, v6
	v_min_f32_e32 v6, v57, v6
	v_max_f32_e32 v57, v2, v7
	v_min_f32_e32 v7, v2, v7
	v_max_f32_e32 v2, v3, v9
	v_min_f32_e32 v9, v3, v9
	v_max_f32_e32 v3, v4, v5
	v_min_f32_e32 v5, v4, v5
	v_max_f32_e32 v4, v8, v15
	v_min_f32_e32 v15, v8, v15
	v_max_f32_e32 v8, v10, v16
	v_min_f32_e32 v16, v10, v16
	v_max_f32_e32 v10, v12, v17
	v_min_f32_e32 v17, v12, v17
	v_max_f32_e32 v12, v13, v14
	v_min_f32_e32 v14, v13, v14
	v_max_f32_e32 v13, v11, v57
	v_min_f32_e32 v57, v11, v57
	v_max_f32_e32 v11, v2, v3
	v_min_f32_e32 v3, v2, v3
	v_max_f32_e32 v2, v5, v6
	v_min_f32_e32 v6, v5, v6
	v_max_f32_e32 v5, v4, v8
	v_min_f32_e32 v8, v4, v8
	v_max_f32_e32 v4, v7, v9
	v_min_f32_e32 v9, v7, v9
	v_max_f32_e32 v7, v10, v12
	v_min_f32_e32 v12, v10, v12
	v_max_f32_e32 v10, v14, v15
	v_min_f32_e32 v15, v14, v15
	v_max_f32_e32 v14, v16, v17
	v_min_f32_e32 v17, v16, v17
	v_max3_f32 v16, v13, v11, v56
	v_min_f32_e32 v11, v13, v11
	v_max_f32_e32 v13, v57, v3
	v_min_f32_e32 v3, v57, v3
	v_max_f32_e32 v56, v2, v7
	v_min_f32_e32 v7, v2, v7
	v_max_f32_e32 v2, v6, v12
	v_min_f32_e32 v12, v6, v12
	v_max_f32_e32 v6, v5, v4
	v_min_f32_e32 v4, v5, v4
	v_max_f32_e32 v5, v8, v9
	v_min_f32_e32 v9, v8, v9
	v_max_f32_e32 v8, v10, v14
	v_min_f32_e32 v14, v10, v14
	v_max_f32_e32 v10, v15, v17
	v_min_f32_e32 v17, v15, v17
	v_max_f32_e32 v15, v13, v11
	v_min_f32_e32 v11, v13, v11
	v_max_f32_e32 v13, v3, v8
	v_min_f32_e32 v8, v3, v8
	v_max_f32_e32 v3, v56, v6
	v_min_f32_e32 v6, v56, v6
	v_max_f32_e32 v56, v2, v4
	v_min_f32_e32 v4, v2, v4
	v_max_f32_e32 v2, v5, v7
	v_min_f32_e32 v7, v5, v7
	v_max_f32_e32 v5, v9, v12
	v_min_f32_e32 v12, v9, v12
	v_max_f32_e32 v9, v10, v14
	v_min_f32_e32 v14, v10, v14
	v_max3_f32 v10, v15, v3, v55
	v_min_f32_e32 v3, v15, v3
	v_max_f32_e32 v15, v11, v6
	v_min_f32_e32 v6, v11, v6
	v_max_f32_e32 v11, v56, v2
	v_min_f32_e32 v2, v56, v2
	v_max_f32_e32 v55, v4, v7
	v_min_f32_e32 v7, v4, v7
	v_max_f32_e32 v4, v5, v9
	v_min_f32_e32 v9, v5, v9
	v_max_f32_e32 v5, v12, v14
	v_min_f32_e32 v14, v12, v14
	v_max3_f32 v12, v15, v3, v54
	v_min_f32_e32 v3, v15, v3
	v_max_f32_e32 v15, v13, v6
	v_min_f32_e32 v6, v13, v6
	v_max_f32_e32 v13, v4, v8
	v_min_f32_e32 v8, v4, v8
	v_max_f32_e32 v4, v5, v9
	v_min_f32_e32 v9, v5, v9
	v_max_f32_e32 v5, v15, v11
	v_min_f32_e32 v11, v15, v11
	v_max_f32_e32 v15, v6, v2
	v_min_f32_e32 v2, v6, v2
	v_max_f32_e32 v6, v55, v13
	v_min_f32_e32 v13, v55, v13
	v_max_f32_e32 v54, v7, v8
	v_min_f32_e32 v8, v7, v8
	v_max3_f32 v7, v5, v3, v53
	v_min_f32_e32 v3, v5, v3
	v_max3_f32 v5, v11, v15, v51
	v_min_f32_e32 v15, v11, v15
	v_max_f32_e32 v11, v6, v2
	v_min_f32_e32 v2, v6, v2
	v_max_f32_e32 v6, v13, v54
	v_min_f32_e32 v54, v13, v54
	v_max3_f32 v13, v4, v8, v229
	v_min_f32_e32 v8, v4, v8
	v_max3_f32 v4, v15, v11, v50
	v_min_f32_e32 v11, v15, v11
	v_max3_f32 v15, v2, v6, v48
	v_min_f32_e32 v6, v2, v6
	v_max_f32_e32 v17, v206, v17
	v_max_f32_e32 v14, v207, v14
	v_max_f32_e32 v9, v227, v9
	v_max_f32_e32 v8, v228, v8
	v_max_f32_e32 v54, v230, v54
	v_max_f32_e32 v6, v231, v6
	v_max_f32_e32 v11, v49, v11
	v_max_f32_e32 v3, v52, v3
	v_max_f32_e32 v2, v16, v15
	v_min_f32_e32 v15, v16, v15
	v_max_f32_e32 v16, v10, v6
	v_min_f32_e32 v6, v10, v6
	v_max_f32_e32 v10, v12, v54
	v_min_f32_e32 v54, v12, v54
	v_max_f32_e32 v12, v7, v13
	v_min_f32_e32 v13, v7, v13
	v_max_f32_e32 v7, v3, v8
	v_min_f32_e32 v8, v3, v8
	v_max_f32_e32 v3, v5, v9
	v_min_f32_e32 v9, v5, v9
	v_max_f32_e32 v5, v4, v14
	v_min_f32_e32 v14, v4, v14
	v_max_f32_e32 v4, v11, v17
	v_min_f32_e32 v17, v11, v17
	v_max_f32_e32 v11, v2, v7
	v_min_f32_e32 v7, v2, v7
	v_max_f32_e32 v2, v16, v3
	v_min_f32_e32 v3, v16, v3
	v_max_f32_e32 v16, v10, v5
	v_min_f32_e32 v5, v10, v5
	v_max_f32_e32 v10, v12, v4
	v_min_f32_e32 v4, v12, v4
	v_max_f32_e32 v12, v15, v8
	v_min_f32_e32 v8, v15, v8
	v_max_f32_e32 v15, v6, v9
	v_min_f32_e32 v9, v6, v9
	v_max_f32_e32 v6, v54, v14
	v_min_f32_e32 v14, v54, v14
	v_max_f32_e32 v206, v13, v17
	v_min_f32_e32 v17, v13, v17
	v_max_f32_e32 v13, v11, v16
	v_min_f32_e32 v16, v11, v16
	v_max_f32_e32 v11, v2, v10
	v_min_f32_e32 v10, v2, v10
	v_max_f32_e32 v2, v7, v5
	v_min_f32_e32 v5, v7, v5
	v_max_f32_e32 v7, v3, v4
	v_min_f32_e32 v4, v3, v4
	v_max_f32_e32 v3, v12, v6
	v_min_f32_e32 v6, v12, v6
	v_max_f32_e32 v12, v15, v206
	v_min_f32_e32 v206, v15, v206
	v_max_f32_e32 v15, v8, v14
	v_min_f32_e32 v14, v8, v14
	v_max_f32_e32 v8, v9, v17
	v_min_f32_e32 v17, v9, v17
	v_max_f32_e32 v57, v13, v11
	v_min_f32_e32 v58, v13, v11
	v_max_f32_e32 v59, v16, v10
	v_min_f32_e32 v60, v16, v10
	v_max_f32_e32 v61, v2, v7
	v_min_f32_e32 v154, v2, v7
	v_max_f32_e32 v205, v5, v4
	v_min_f32_e32 v48, v5, v4
	v_max_f32_e32 v49, v3, v12
	v_min_f32_e32 v50, v3, v12
	v_max_f32_e32 v51, v6, v206
	v_min_f32_e32 v52, v6, v206
	v_max_f32_e32 v53, v15, v8
	v_min_f32_e32 v54, v15, v8
	v_max_f32_e32 v55, v14, v17
	v_min_f32_e32 v56, v14, v17
	s_waitcnt vmcnt(0)
	v_mfma_f32_32x32x16_bf16 v[2:17], v[232:235], v[30:33], 0
	v_mfma_f32_32x32x16_bf16 v[2:17], v[42:45], v[26:29], v[2:17]
	v_mfma_f32_32x32x16_bf16 v[2:17], v[38:41], v[22:25], v[2:17]
	v_mfma_f32_32x32x16_bf16 v[2:17], v[34:37], v[18:21], v[2:17]
	s_nop 11
	v_and_or_b32 v2, v2, s33, v189
	v_and_or_b32 v3, v3, s33, v190
	v_and_or_b32 v4, v4, s33, v191
	v_and_or_b32 v5, v5, s33, v192
	v_and_or_b32 v6, v6, s33, v193
	v_and_or_b32 v7, v7, s33, v194
	v_and_or_b32 v8, v8, s33, v195
	v_and_or_b32 v9, v9, s33, v196
	v_and_or_b32 v10, v10, s33, v197
	v_and_or_b32 v11, v11, s33, v198
	v_and_or_b32 v12, v12, s33, v199
	v_and_or_b32 v13, v13, s33, v200
	v_and_or_b32 v14, v14, s33, v201
	v_and_or_b32 v15, v15, s33, v202
	v_and_or_b32 v16, v16, s33, v203
	v_and_or_b32 v17, v17, s33, v204
	v_max_f32_e32 v19, v2, v15
	v_min_f32_e32 v15, v2, v15
	v_max_f32_e32 v20, v3, v14
	v_min_f32_e32 v14, v3, v14
	v_max_f32_e32 v21, v4, v17
	v_min_f32_e32 v17, v4, v17
	v_max_f32_e32 v22, v5, v16
	v_min_f32_e32 v16, v5, v16
	v_max_f32_e32 v23, v6, v10
	v_min_f32_e32 v10, v6, v10
	v_max_f32_e32 v24, v7, v8
	v_min_f32_e32 v8, v7, v8
	v_max_f32_e32 v25, v9, v13
	v_min_f32_e32 v13, v9, v13
	v_max_f32_e32 v26, v11, v12
	v_min_f32_e32 v12, v11, v12
	v_max_f32_e32 v27, v19, v24
	v_min_f32_e32 v24, v19, v24
	v_max_f32_e32 v19, v20, v25
	v_min_f32_e32 v25, v20, v25
	v_max_f32_e32 v20, v21, v26
	v_min_f32_e32 v26, v21, v26
	v_max_f32_e32 v21, v22, v23
	v_min_f32_e32 v23, v22, v23
	v_max_f32_e32 v22, v8, v15
	v_min_f32_e32 v15, v8, v15
	v_max_f32_e32 v28, v10, v16
	v_min_f32_e32 v16, v10, v16
	v_max_f32_e32 v29, v12, v17
	v_min_f32_e32 v17, v12, v17
	v_max_f32_e32 v30, v13, v14
	v_min_f32_e32 v14, v13, v14
	v_max_f32_e32 v31, v27, v19
	v_min_f32_e32 v19, v27, v19
	v_max_f32_e32 v27, v20, v21
	v_min_f32_e32 v21, v20, v21
	v_max_f32_e32 v20, v23, v24
	v_min_f32_e32 v24, v23, v24
	v_max_f32_e32 v23, v22, v28
	v_min_f32_e32 v28, v22, v28
	v_max_f32_e32 v22, v25, v26
	v_min_f32_e32 v26, v25, v26
	v_max_f32_e32 v25, v29, v30
	v_min_f32_e32 v30, v29, v30
	v_max_f32_e32 v29, v14, v15
	v_min_f32_e32 v15, v14, v15
	v_max_f32_e32 v32, v16, v17
	v_min_f32_e32 v17, v16, v17
	v_max3_f32 v2, v31, v27, v56
	v_min_f32_e32 v27, v31, v27
	v_max_f32_e32 v31, v19, v21
	v_min_f32_e32 v21, v19, v21
	v_max_f32_e32 v19, v20, v25
	v_min_f32_e32 v25, v20, v25
	v_max_f32_e32 v20, v24, v30
	v_min_f32_e32 v30, v24, v30
	v_max_f32_e32 v24, v23, v22
	v_min_f32_e32 v22, v23, v22
	v_max_f32_e32 v23, v28, v26
	v_min_f32_e32 v26, v28, v26
	v_max_f32_e32 v28, v29, v32
	v_min_f32_e32 v32, v29, v32
	v_max_f32_e32 v29, v15, v17
	v_min_f32_e32 v17, v15, v17
	v_max_f32_e32 v3, v31, v27
	v_min_f32_e32 v27, v31, v27
	v_max_f32_e32 v31, v21, v28
	v_min_f32_e32 v28, v21, v28
	v_max_f32_e32 v21, v19, v24
	v_min_f32_e32 v24, v19, v24
	v_max_f32_e32 v19, v20, v22
	v_min_f32_e32 v22, v20, v22
	v_max_f32_e32 v20, v23, v25
	v_min_f32_e32 v25, v23, v25
	v_max_f32_e32 v23, v26, v30
	v_min_f32_e32 v30, v26, v30
	v_max_f32_e32 v26, v29, v32
	v_min_f32_e32 v32, v29, v32
	v_max3_f32 v29, v3, v21, v55
	v_min_f32_e32 v21, v3, v21
	v_max_f32_e32 v3, v27, v24
	v_min_f32_e32 v24, v27, v24
	v_max_f32_e32 v27, v19, v20
	v_min_f32_e32 v20, v19, v20
	v_max_f32_e32 v19, v22, v25
	v_min_f32_e32 v25, v22, v25
	v_max_f32_e32 v22, v23, v26
	v_min_f32_e32 v26, v23, v26
	v_max_f32_e32 v23, v30, v32
	v_min_f32_e32 v32, v30, v32
	v_max3_f32 v30, v3, v21, v54
	v_min_f32_e32 v21, v3, v21
	v_max_f32_e32 v3, v31, v24
	v_min_f32_e32 v24, v31, v24
	v_max_f32_e32 v31, v22, v28
	v_min_f32_e32 v28, v22, v28
	v_max_f32_e32 v22, v23, v26
	v_min_f32_e32 v26, v23, v26
	v_max_f32_e32 v23, v3, v27
	v_min_f32_e32 v27, v3, v27
	v_max_f32_e32 v3, v24, v20
	v_min_f32_e32 v20, v24, v20
	v_max_f32_e32 v24, v19, v31
	v_min_f32_e32 v31, v19, v31
	v_max_f32_e32 v19, v25, v28
	v_min_f32_e32 v28, v25, v28
	v_max3_f32 v25, v23, v21, v53
	v_min_f32_e32 v21, v23, v21
	v_max3_f32 v23, v27, v3, v51
	v_min_f32_e32 v3, v27, v3
	v_max_f32_e32 v27, v24, v20
	v_min_f32_e32 v20, v24, v20
	v_max_f32_e32 v24, v31, v19
	v_min_f32_e32 v19, v31, v19
	v_max3_f32 v31, v22, v28, v61
	v_min_f32_e32 v28, v22, v28
	v_max3_f32 v22, v3, v27, v50
	v_min_f32_e32 v27, v3, v27
	v_max3_f32 v3, v20, v24, v48
	v_min_f32_e32 v24, v20, v24
	v_max_f32_e32 v17, v57, v17
	v_max_f32_e32 v32, v58, v32
	v_max_f32_e32 v26, v59, v26
	v_max_f32_e32 v28, v60, v28
	v_max_f32_e32 v19, v154, v19
	v_max_f32_e32 v24, v205, v24
	v_max_f32_e32 v27, v49, v27
	v_max_f32_e32 v21, v52, v21
	v_max_f32_e32 v20, v2, v3
	v_min_f32_e32 v3, v2, v3
	v_max_f32_e32 v2, v29, v24
	v_min_f32_e32 v24, v29, v24
	v_max_f32_e32 v29, v30, v19
	v_min_f32_e32 v19, v30, v19
	v_max_f32_e32 v30, v25, v31
	v_min_f32_e32 v31, v25, v31
	v_max_f32_e32 v25, v21, v28
	v_min_f32_e32 v28, v21, v28
	v_max_f32_e32 v21, v23, v26
	v_min_f32_e32 v26, v23, v26
	v_max_f32_e32 v23, v22, v32
	v_min_f32_e32 v32, v22, v32
	v_max_f32_e32 v22, v27, v17
	v_min_f32_e32 v17, v27, v17
	v_max_f32_e32 v27, v20, v25
	v_min_f32_e32 v25, v20, v25
	v_max_f32_e32 v20, v2, v21
	v_min_f32_e32 v21, v2, v21
	v_max_f32_e32 v2, v29, v23
	v_min_f32_e32 v23, v29, v23
	v_max_f32_e32 v29, v30, v22
	v_min_f32_e32 v22, v30, v22
	v_max_f32_e32 v30, v3, v28
	v_min_f32_e32 v28, v3, v28
	v_max_f32_e32 v3, v24, v26
	v_min_f32_e32 v26, v24, v26
	v_max_f32_e32 v24, v19, v32
	v_min_f32_e32 v32, v19, v32
	v_max_f32_e32 v19, v31, v17
	v_min_f32_e32 v17, v31, v17
	v_max_f32_e32 v31, v27, v2
	v_min_f32_e32 v2, v27, v2
	v_max_f32_e32 v27, v20, v29
	v_min_f32_e32 v29, v20, v29
	v_max_f32_e32 v20, v25, v23
	v_min_f32_e32 v23, v25, v23
	v_max_f32_e32 v25, v21, v22
	v_min_f32_e32 v22, v21, v22
	v_max_f32_e32 v21, v30, v24
	v_min_f32_e32 v24, v30, v24
	v_max_f32_e32 v30, v3, v19
	v_min_f32_e32 v19, v3, v19
	v_max_f32_e32 v3, v28, v32
	v_min_f32_e32 v32, v28, v32
	v_max_f32_e32 v28, v26, v17
	v_min_f32_e32 v17, v26, v17
	v_max_f32_e32 v15, v31, v27
	v_min_f32_e32 v27, v31, v27
	v_max_f32_e32 v12, v2, v29
	v_min_f32_e32 v5, v2, v29
	v_max_f32_e32 v9, v20, v25
	v_min_f32_e32 v25, v20, v25
	v_max_f32_e32 v18, v23, v22
	v_min_f32_e32 v4, v23, v22
	v_max_f32_e32 v11, v21, v30
	v_min_f32_e32 v13, v21, v30
	v_max_f32_e32 v16, v24, v19
	v_min_f32_e32 v7, v24, v19
	v_max_f32_e32 v14, v3, v28
	v_min_f32_e32 v8, v3, v28
	v_max_f32_e32 v10, v32, v17
	v_min_f32_e32 v2, v32, v17
	v_mov_b32_e32 v3, v27
	v_mov_b32_e32 v17, v25
	ds_bpermute_b32 v6, v121, v15
	ds_bpermute_b32 v19, v121, v3
	ds_bpermute_b32 v20, v121, v12
	ds_bpermute_b32 v21, v121, v5
	ds_bpermute_b32 v22, v121, v9
	ds_bpermute_b32 v23, v121, v17
	ds_bpermute_b32 v24, v121, v18
	ds_bpermute_b32 v25, v121, v4
	ds_bpermute_b32 v26, v121, v11
	ds_bpermute_b32 v27, v121, v13
	ds_bpermute_b32 v28, v121, v16
	ds_bpermute_b32 v29, v121, v7
	ds_bpermute_b32 v30, v121, v14
	ds_bpermute_b32 v31, v121, v8
	ds_bpermute_b32 v32, v121, v10
	ds_bpermute_b32 v33, v121, v2
	s_waitcnt lgkmcnt(4)
	s_waitcnt lgkmcnt(3)
	s_waitcnt lgkmcnt(2)
	s_waitcnt lgkmcnt(1)
	s_waitcnt lgkmcnt(0)
	v_max_f32_e32 v15, v15, v33
	v_max_f32_e32 v3, v3, v32
	v_max_f32_e32 v12, v12, v31
	v_max_f32_e32 v5, v5, v30
	v_max_f32_e32 v9, v9, v29
	v_max_f32_e32 v17, v17, v28
	v_max_f32_e32 v18, v18, v27
	v_max_f32_e32 v4, v4, v26
	v_max_f32_e32 v11, v11, v25
	v_max_f32_e32 v13, v13, v24
	v_max_f32_e32 v16, v16, v23
	v_max_f32_e32 v7, v7, v22
	v_max_f32_e32 v14, v14, v21
	v_max_f32_e32 v8, v8, v20
	v_max_f32_e32 v10, v10, v19
	v_max_f32_e32 v2, v2, v6
	v_max_f32_e32 v6, v15, v11
	v_min_f32_e32 v11, v15, v11
	v_max_f32_e32 v15, v3, v13
	v_min_f32_e32 v3, v3, v13
	v_max_f32_e32 v13, v12, v16
	v_min_f32_e32 v12, v12, v16
	v_max_f32_e32 v16, v5, v7
	v_min_f32_e32 v5, v5, v7
	v_max_f32_e32 v7, v9, v14
	v_min_f32_e32 v9, v9, v14
	v_max_f32_e32 v14, v17, v8
	v_min_f32_e32 v8, v17, v8
	v_max_f32_e32 v17, v18, v10
	v_min_f32_e32 v10, v18, v10
	v_max_f32_e32 v18, v4, v2
	v_min_f32_e32 v2, v4, v2
	v_max_f32_e32 v4, v6, v7
	v_min_f32_e32 v6, v6, v7
	v_max_f32_e32 v7, v15, v14
	v_min_f32_e32 v14, v15, v14
	v_max_f32_e32 v15, v13, v17
	v_min_f32_e32 v13, v13, v17
	v_max_f32_e32 v17, v16, v18
	v_min_f32_e32 v16, v16, v18
	v_max_f32_e32 v18, v11, v9
	v_min_f32_e32 v9, v11, v9
	v_max_f32_e32 v11, v3, v8
	v_min_f32_e32 v3, v3, v8
	v_max_f32_e32 v8, v12, v10
	v_min_f32_e32 v10, v12, v10
	v_max_f32_e32 v12, v5, v2
	v_min_f32_e32 v2, v5, v2
	v_max_f32_e32 v5, v4, v15
	v_min_f32_e32 v4, v4, v15
	v_max_f32_e32 v15, v7, v17
	v_min_f32_e32 v7, v7, v17
	v_max_f32_e32 v17, v6, v13
	v_min_f32_e32 v6, v6, v13
	v_max_f32_e32 v13, v14, v16
	v_min_f32_e32 v14, v14, v16
	v_max_f32_e32 v16, v18, v8
	v_min_f32_e32 v8, v18, v8
	v_max_f32_e32 v18, v11, v12
	v_min_f32_e32 v11, v11, v12
	v_max_f32_e32 v12, v9, v10
	v_min_f32_e32 v9, v9, v10
	v_max_f32_e32 v10, v3, v2
	v_min_f32_e32 v2, v3, v2
	v_max_f32_e32 v20, v9, v2
	v_min_f32_e32 v21, v9, v2
	v_lshl_add_u64 v[2:3], v[64:65], 0, v[46:47]
	v_max_f32_e32 v30, v5, v15
	v_min_f32_e32 v31, v5, v15
	v_max_f32_e32 v32, v4, v7
	v_min_f32_e32 v33, v4, v7
	global_load_dwordx4 v[46:49], v[2:3], off
	global_load_dwordx4 v[42:45], v[2:3], off offset:32
	global_load_dwordx4 v[38:41], v[2:3], off offset:64
	global_load_dwordx4 v[34:37], v[2:3], off offset:96
	s_nop 0
	global_load_dwordx4 v[2:5], v[90:91], off
	global_load_dwordx4 v[58:61], v[90:91], off offset:32
	global_load_dwordx4 v[54:57], v[90:91], off offset:64
	global_load_dwordx4 v[50:53], v[90:91], off offset:96
	v_max_f32_e32 v26, v17, v13
	v_min_f32_e32 v27, v17, v13
	v_max_f32_e32 v28, v6, v14
	v_min_f32_e32 v29, v6, v14
	v_max_f32_e32 v22, v16, v18
	v_min_f32_e32 v23, v16, v18
	v_max_f32_e32 v24, v8, v11
	v_min_f32_e32 v25, v8, v11
	v_max_f32_e32 v18, v12, v10
	v_min_f32_e32 v19, v12, v10
	s_waitcnt vmcnt(3)
	v_mfma_f32_32x32x16_bf16 v[2:17], v[2:5], v[46:49], 0
	s_waitcnt vmcnt(2)
	v_mfma_f32_32x32x16_bf16 v[2:17], v[58:61], v[42:45], v[2:17]
	s_waitcnt vmcnt(1)
	v_mfma_f32_32x32x16_bf16 v[2:17], v[54:57], v[38:41], v[2:17]
	s_waitcnt vmcnt(0)
	v_mfma_f32_32x32x16_bf16 v[2:17], v[50:53], v[34:37], v[2:17]
	s_nop 11
	v_and_or_b32 v2, v2, s33, v120
	v_and_or_b32 v3, v3, s33, v122
	v_and_or_b32 v4, v4, s33, v123
	v_and_or_b32 v5, v5, s33, v124
	v_and_or_b32 v6, v6, s33, v125
	v_and_or_b32 v7, v7, s33, v126
	v_and_or_b32 v8, v8, s33, v127
	v_and_or_b32 v9, v9, s33, v128
	v_and_or_b32 v10, v10, s33, v129
	v_and_or_b32 v11, v11, s33, v136
	v_and_or_b32 v12, v12, s33, v137
	v_and_or_b32 v13, v13, s33, v138
	v_and_or_b32 v14, v14, s33, v139
	v_and_or_b32 v15, v15, s33, v140
	v_and_or_b32 v16, v16, s33, v141
	v_and_or_b32 v17, v17, s33, v142
	global_load_dwordx4 v[50:53], v[92:93], off offset:96
	global_load_dwordx4 v[54:57], v[92:93], off offset:64
	global_load_dwordx4 v[58:61], v[92:93], off offset:32
	global_load_dwordx4 v[244:247], v[92:93], off
	v_max_f32_e32 v239, v2, v15
	v_min_f32_e32 v15, v2, v15
	v_max_f32_e32 v240, v3, v14
	v_min_f32_e32 v14, v3, v14
	v_max_f32_e32 v241, v4, v17
	v_min_f32_e32 v17, v4, v17
	v_max_f32_e32 v242, v5, v16
	v_min_f32_e32 v16, v5, v16
	v_max_f32_e32 v243, v6, v10
	v_min_f32_e32 v10, v6, v10
	v_max_f32_e32 v2, v7, v8
	v_min_f32_e32 v8, v7, v8
	v_max_f32_e32 v3, v9, v13
	v_min_f32_e32 v13, v9, v13
	v_max_f32_e32 v4, v11, v12
	v_min_f32_e32 v12, v11, v12
	v_max_f32_e32 v5, v239, v2
	v_min_f32_e32 v2, v239, v2
	v_max_f32_e32 v239, v240, v3
	v_min_f32_e32 v3, v240, v3
	v_max_f32_e32 v240, v241, v4
	v_min_f32_e32 v4, v241, v4
	v_max_f32_e32 v241, v242, v243
	v_min_f32_e32 v243, v242, v243
	v_max_f32_e32 v242, v8, v15
	v_min_f32_e32 v15, v8, v15
	v_max_f32_e32 v6, v10, v16
	v_min_f32_e32 v16, v10, v16
	v_max_f32_e32 v7, v12, v17
	v_min_f32_e32 v17, v12, v17
	v_max_f32_e32 v8, v13, v14
	v_min_f32_e32 v14, v13, v14
	v_max_f32_e32 v9, v5, v239
	v_min_f32_e32 v239, v5, v239
	v_max_f32_e32 v5, v240, v241
	v_min_f32_e32 v241, v240, v241
	v_max_f32_e32 v240, v243, v2
	v_min_f32_e32 v2, v243, v2
	v_max_f32_e32 v243, v242, v6
	v_min_f32_e32 v6, v242, v6
	v_max_f32_e32 v242, v3, v4
	v_min_f32_e32 v4, v3, v4
	v_max_f32_e32 v3, v7, v8
	v_min_f32_e32 v8, v7, v8
	v_max_f32_e32 v7, v14, v15
	v_min_f32_e32 v15, v14, v15
	v_max_f32_e32 v10, v16, v17
	v_min_f32_e32 v17, v16, v17
	v_max_f32_e32 v154, v9, v5
	v_min_f32_e32 v5, v9, v5
	v_max_f32_e32 v9, v239, v241
	v_min_f32_e32 v241, v239, v241
	v_max_f32_e32 v239, v240, v3
	v_min_f32_e32 v3, v240, v3
	v_max_f32_e32 v240, v2, v8
	v_min_f32_e32 v8, v2, v8
	v_max_f32_e32 v2, v243, v242
	v_min_f32_e32 v242, v243, v242
	v_max_f32_e32 v243, v6, v4
	v_min_f32_e32 v4, v6, v4
	v_max_f32_e32 v6, v7, v10
	v_min_f32_e32 v10, v7, v10
	v_min_f32_e32 v238, v15, v17
	v_max_f32_e32 v15, v15, v17
	v_max_f32_e32 v7, v9, v5
	v_min_f32_e32 v5, v9, v5
	v_max_f32_e32 v9, v241, v6
	v_min_f32_e32 v6, v241, v6
	v_max_f32_e32 v241, v239, v2
	v_min_f32_e32 v2, v239, v2
	v_max_f32_e32 v239, v240, v242
	v_min_f32_e32 v242, v240, v242
	v_max_f32_e32 v240, v243, v3
	v_min_f32_e32 v3, v243, v3
	v_max_f32_e32 v243, v4, v8
	v_min_f32_e32 v8, v4, v8
	v_max_f32_e32 v4, v15, v10
	v_min_f32_e32 v10, v15, v10
	v_max_f32_e32 v205, v7, v241
	v_min_f32_e32 v241, v7, v241
	v_max_f32_e32 v7, v5, v2
	v_min_f32_e32 v2, v5, v2
	v_max_f32_e32 v5, v239, v240
	v_min_f32_e32 v240, v239, v240
	v_max_f32_e32 v239, v242, v3
	v_min_f32_e32 v3, v242, v3
	v_max_f32_e32 v242, v243, v4
	v_min_f32_e32 v4, v243, v4
	v_min_f32_e32 v237, v8, v10
	v_max_f32_e32 v8, v8, v10
	v_max_f32_e32 v206, v7, v241
	v_min_f32_e32 v241, v7, v241
	v_max_f32_e32 v243, v9, v2
	v_min_f32_e32 v2, v9, v2
	v_max_f32_e32 v7, v242, v6
	v_min_f32_e32 v6, v242, v6
	v_min_f32_e32 v236, v8, v4
	v_max_f32_e32 v8, v8, v4
	v_max_f32_e32 v242, v243, v5
	v_min_f32_e32 v5, v243, v5
	v_max_f32_e32 v243, v2, v240
	v_min_f32_e32 v240, v2, v240
	v_max_f32_e32 v2, v239, v7
	v_min_f32_e32 v7, v239, v7
	v_max_f32_e32 v239, v3, v6
	v_min_f32_e32 v6, v3, v6
	v_max_f32_e32 v207, v242, v241
	v_min_f32_e32 v227, v242, v241
	v_max_f32_e32 v228, v5, v243
	v_min_f32_e32 v243, v5, v243
	v_max_f32_e32 v241, v2, v240
	v_min_f32_e32 v240, v2, v240
	v_min_f32_e32 v233, v7, v239
	v_max_f32_e32 v7, v7, v239
	v_max_f32_e32 v234, v8, v6
	v_min_f32_e32 v235, v8, v6
	v_max_f32_e32 v229, v243, v241
	v_min_f32_e32 v230, v243, v241
	v_max_f32_e32 v231, v240, v7
	v_min_f32_e32 v232, v240, v7
	s_waitcnt vmcnt(0)
	v_mfma_f32_32x32x16_bf16 v[2:17], v[244:247], v[46:49], 0
	v_mfma_f32_32x32x16_bf16 v[2:17], v[58:61], v[42:45], v[2:17]
	v_mfma_f32_32x32x16_bf16 v[2:17], v[54:57], v[38:41], v[2:17]
	v_mfma_f32_32x32x16_bf16 v[2:17], v[50:53], v[34:37], v[2:17]
	s_nop 11
	v_and_or_b32 v2, v2, s33, v143
	v_and_or_b32 v3, v3, s33, v144
	v_and_or_b32 v4, v4, s33, v145
	v_and_or_b32 v5, v5, s33, v146
	v_and_or_b32 v6, v6, s33, v147
	v_and_or_b32 v7, v7, s33, v148
	v_and_or_b32 v8, v8, s33, v149
	v_and_or_b32 v9, v9, s33, v150
	v_and_or_b32 v10, v10, s33, v151
	v_and_or_b32 v11, v11, s33, v152
	v_and_or_b32 v12, v12, s33, v153
	v_and_or_b32 v13, v13, s33, v160
	v_and_or_b32 v14, v14, s33, v161
	v_and_or_b32 v15, v15, s33, v162
	v_and_or_b32 v16, v16, s33, v163
	v_and_or_b32 v17, v17, s33, v164
	global_load_dwordx4 v[50:53], v[94:95], off offset:96
	global_load_dwordx4 v[54:57], v[94:95], off offset:64
	global_load_dwordx4 v[58:61], v[94:95], off offset:32
	global_load_dwordx4 v[244:247], v[94:95], off
	v_max_f32_e32 v239, v2, v15
	v_min_f32_e32 v15, v2, v15
	v_max_f32_e32 v2, v3, v14
	v_min_f32_e32 v14, v3, v14
	v_max_f32_e32 v3, v4, v17
	v_min_f32_e32 v17, v4, v17
	v_max_f32_e32 v4, v5, v16
	v_min_f32_e32 v16, v5, v16
	v_max_f32_e32 v5, v6, v10
	v_min_f32_e32 v10, v6, v10
	v_max_f32_e32 v6, v7, v8
	v_min_f32_e32 v8, v7, v8
	v_max_f32_e32 v7, v9, v13
	v_min_f32_e32 v13, v9, v13
	v_max_f32_e32 v9, v11, v12
	v_min_f32_e32 v12, v11, v12
	v_max_f32_e32 v11, v239, v6
	v_min_f32_e32 v6, v239, v6
	v_max_f32_e32 v239, v2, v7
	v_min_f32_e32 v7, v2, v7
	v_max_f32_e32 v2, v3, v9
	v_min_f32_e32 v9, v3, v9
	v_max_f32_e32 v3, v4, v5
	v_min_f32_e32 v5, v4, v5
	v_max_f32_e32 v4, v8, v15
	v_min_f32_e32 v15, v8, v15
	v_max_f32_e32 v8, v10, v16
	v_min_f32_e32 v16, v10, v16
	v_max_f32_e32 v10, v12, v17
	v_min_f32_e32 v17, v12, v17
	v_max_f32_e32 v12, v13, v14
	v_min_f32_e32 v14, v13, v14
	v_max_f32_e32 v13, v11, v239
	v_min_f32_e32 v239, v11, v239
	v_max_f32_e32 v11, v2, v3
	v_min_f32_e32 v3, v2, v3
	v_max_f32_e32 v2, v5, v6
	v_min_f32_e32 v6, v5, v6
	v_max_f32_e32 v5, v4, v8
	v_min_f32_e32 v8, v4, v8
	v_max_f32_e32 v4, v7, v9
	v_min_f32_e32 v9, v7, v9
	v_max_f32_e32 v7, v10, v12
	v_min_f32_e32 v12, v10, v12
	v_max_f32_e32 v10, v14, v15
	v_min_f32_e32 v15, v14, v15
	v_max_f32_e32 v14, v16, v17
	v_min_f32_e32 v17, v16, v17
	v_max3_f32 v16, v13, v11, v238
	v_min_f32_e32 v11, v13, v11
	v_max_f32_e32 v13, v239, v3
	v_min_f32_e32 v3, v239, v3
	v_max_f32_e32 v238, v2, v7
	v_min_f32_e32 v7, v2, v7
	v_max_f32_e32 v2, v6, v12
	v_min_f32_e32 v12, v6, v12
	v_max_f32_e32 v6, v5, v4
	v_min_f32_e32 v4, v5, v4
	v_max_f32_e32 v5, v8, v9
	v_min_f32_e32 v9, v8, v9
	v_max_f32_e32 v8, v10, v14
	v_min_f32_e32 v14, v10, v14
	v_max_f32_e32 v10, v15, v17
	v_min_f32_e32 v17, v15, v17
	v_max_f32_e32 v15, v13, v11
	v_min_f32_e32 v11, v13, v11
	v_max_f32_e32 v13, v3, v8
	v_min_f32_e32 v8, v3, v8
	v_max_f32_e32 v3, v238, v6
	v_min_f32_e32 v6, v238, v6
	v_max_f32_e32 v238, v2, v4
	v_min_f32_e32 v4, v2, v4
	v_max_f32_e32 v2, v5, v7
	v_min_f32_e32 v7, v5, v7
	v_max_f32_e32 v5, v9, v12
	v_min_f32_e32 v12, v9, v12
	v_max_f32_e32 v9, v10, v14
	v_min_f32_e32 v14, v10, v14
	v_max3_f32 v10, v15, v3, v237
	v_min_f32_e32 v3, v15, v3
	v_max_f32_e32 v15, v11, v6
	v_min_f32_e32 v6, v11, v6
	v_max_f32_e32 v11, v238, v2
	v_min_f32_e32 v2, v238, v2
	v_max_f32_e32 v237, v4, v7
	v_min_f32_e32 v7, v4, v7
	v_max_f32_e32 v4, v5, v9
	v_min_f32_e32 v9, v5, v9
	v_max_f32_e32 v5, v12, v14
	v_min_f32_e32 v14, v12, v14
	v_max3_f32 v12, v15, v3, v236
	v_min_f32_e32 v3, v15, v3
	v_max_f32_e32 v15, v13, v6
	v_min_f32_e32 v6, v13, v6
	v_max_f32_e32 v13, v4, v8
	v_min_f32_e32 v8, v4, v8
	v_max_f32_e32 v4, v5, v9
	v_min_f32_e32 v9, v5, v9
	v_max_f32_e32 v5, v15, v11
	v_min_f32_e32 v11, v15, v11
	v_max_f32_e32 v15, v6, v2
	v_min_f32_e32 v2, v6, v2
	v_max_f32_e32 v6, v237, v13
	v_min_f32_e32 v13, v237, v13
	v_max_f32_e32 v236, v7, v8
	v_min_f32_e32 v8, v7, v8
	v_max3_f32 v7, v5, v3, v235
	v_min_f32_e32 v3, v5, v3
	v_max3_f32 v5, v11, v15, v233
	v_min_f32_e32 v15, v11, v15
	v_max_f32_e32 v11, v6, v2
	v_min_f32_e32 v2, v6, v2
	v_max_f32_e32 v6, v13, v236
	v_min_f32_e32 v236, v13, v236
	v_max3_f32 v13, v4, v8, v227
	v_min_f32_e32 v8, v4, v8
	v_max3_f32 v4, v15, v11, v232
	v_min_f32_e32 v11, v15, v11
	v_max3_f32 v15, v2, v6, v230
	v_min_f32_e32 v6, v2, v6
	v_max_f32_e32 v17, v154, v17
	v_max_f32_e32 v14, v205, v14
	v_max_f32_e32 v9, v206, v9
	v_max_f32_e32 v8, v207, v8
	v_max_f32_e32 v236, v228, v236
	v_max_f32_e32 v6, v229, v6
	v_max_f32_e32 v11, v231, v11
	v_max_f32_e32 v3, v234, v3
	v_max_f32_e32 v2, v16, v15
	v_min_f32_e32 v15, v16, v15
	v_max_f32_e32 v16, v10, v6
	v_min_f32_e32 v6, v10, v6
	v_max_f32_e32 v10, v12, v236
	v_min_f32_e32 v236, v12, v236
	v_max_f32_e32 v12, v7, v13
	v_min_f32_e32 v13, v7, v13
	v_max_f32_e32 v7, v3, v8
	v_min_f32_e32 v8, v3, v8
	v_max_f32_e32 v3, v5, v9
	v_min_f32_e32 v9, v5, v9
	v_max_f32_e32 v5, v4, v14
	v_min_f32_e32 v14, v4, v14
	v_max_f32_e32 v4, v11, v17
	v_min_f32_e32 v17, v11, v17
	v_max_f32_e32 v11, v2, v7
	v_min_f32_e32 v7, v2, v7
	v_max_f32_e32 v2, v16, v3
	v_min_f32_e32 v3, v16, v3
	v_max_f32_e32 v16, v10, v5
	v_min_f32_e32 v5, v10, v5
	v_max_f32_e32 v10, v12, v4
	v_min_f32_e32 v4, v12, v4
	v_max_f32_e32 v12, v15, v8
	v_min_f32_e32 v8, v15, v8
	v_max_f32_e32 v15, v6, v9
	v_min_f32_e32 v9, v6, v9
	v_max_f32_e32 v6, v236, v14
	v_min_f32_e32 v14, v236, v14
	v_max_f32_e32 v154, v13, v17
	v_min_f32_e32 v17, v13, v17
	v_max_f32_e32 v13, v11, v16
	v_min_f32_e32 v16, v11, v16
	v_max_f32_e32 v11, v2, v10
	v_min_f32_e32 v10, v2, v10
	v_max_f32_e32 v2, v7, v5
	v_min_f32_e32 v5, v7, v5
	v_max_f32_e32 v7, v3, v4
	v_min_f32_e32 v4, v3, v4
	v_max_f32_e32 v3, v12, v6
	v_min_f32_e32 v6, v12, v6
	v_max_f32_e32 v12, v15, v154
	v_min_f32_e32 v154, v15, v154
	v_max_f32_e32 v15, v8, v14
	v_min_f32_e32 v14, v8, v14
	v_max_f32_e32 v8, v9, v17
	v_min_f32_e32 v17, v9, v17
	v_max_f32_e32 v239, v13, v11
	v_min_f32_e32 v240, v13, v11
	v_max_f32_e32 v241, v16, v10
	v_min_f32_e32 v242, v16, v10
	v_max_f32_e32 v243, v2, v7
	v_min_f32_e32 v252, v2, v7
	v_max_f32_e32 v253, v5, v4
	v_min_f32_e32 v4, v5, v4
	v_max_f32_e32 v205, v3, v12
	v_min_f32_e32 v206, v3, v12
	v_max_f32_e32 v207, v6, v154
	v_min_f32_e32 v227, v6, v154
	v_max_f32_e32 v228, v15, v8
	v_min_f32_e32 v229, v15, v8
	v_max_f32_e32 v230, v14, v17
	v_min_f32_e32 v231, v14, v17
	v_mov_b32_e32 v154, v4
	s_waitcnt vmcnt(0)
	v_mfma_f32_32x32x16_bf16 v[2:17], v[244:247], v[46:49], 0
	v_mfma_f32_32x32x16_bf16 v[2:17], v[58:61], v[42:45], v[2:17]
	v_mfma_f32_32x32x16_bf16 v[2:17], v[54:57], v[38:41], v[2:17]
	v_mfma_f32_32x32x16_bf16 v[2:17], v[50:53], v[34:37], v[2:17]
	s_nop 11
	v_and_or_b32 v2, v2, s33, v165
	v_and_or_b32 v3, v3, s33, v166
	v_and_or_b32 v4, v4, s33, v167
	v_and_or_b32 v5, v5, s33, v168
	v_and_or_b32 v6, v6, s33, v169
	v_and_or_b32 v7, v7, s33, v170
	v_and_or_b32 v8, v8, s33, v171
	v_and_or_b32 v9, v9, s33, v172
	v_and_or_b32 v10, v10, s33, v173
	v_and_or_b32 v11, v11, s33, v174
	v_and_or_b32 v12, v12, s33, v175
	v_and_or_b32 v13, v13, s33, v184
	v_and_or_b32 v14, v14, s33, v185
	v_and_or_b32 v15, v15, s33, v186
	v_and_or_b32 v16, v16, s33, v187
	v_and_or_b32 v17, v17, s33, v188
	global_load_dwordx4 v[50:53], v[96:97], off offset:96
	global_load_dwordx4 v[54:57], v[96:97], off offset:64
	global_load_dwordx4 v[58:61], v[96:97], off offset:32
	global_load_dwordx4 v[244:247], v[96:97], off
	v_max_f32_e32 v232, v2, v15
	v_min_f32_e32 v15, v2, v15
	v_max_f32_e32 v2, v3, v14
	v_min_f32_e32 v14, v3, v14
	v_max_f32_e32 v3, v4, v17
	v_min_f32_e32 v17, v4, v17
	v_max_f32_e32 v4, v5, v16
	v_min_f32_e32 v16, v5, v16
	v_max_f32_e32 v5, v6, v10
	v_min_f32_e32 v10, v6, v10
	v_max_f32_e32 v6, v7, v8
	v_min_f32_e32 v8, v7, v8
	v_max_f32_e32 v7, v9, v13
	v_min_f32_e32 v13, v9, v13
	v_max_f32_e32 v9, v11, v12
	v_min_f32_e32 v12, v11, v12
	v_max_f32_e32 v11, v232, v6
	v_min_f32_e32 v6, v232, v6
	v_max_f32_e32 v232, v2, v7
	v_min_f32_e32 v7, v2, v7
	v_max_f32_e32 v2, v3, v9
	v_min_f32_e32 v9, v3, v9
	v_max_f32_e32 v3, v4, v5
	v_min_f32_e32 v5, v4, v5
	v_max_f32_e32 v4, v8, v15
	v_min_f32_e32 v15, v8, v15
	v_max_f32_e32 v8, v10, v16
	v_min_f32_e32 v16, v10, v16
	v_max_f32_e32 v10, v12, v17
	v_min_f32_e32 v17, v12, v17
	v_max_f32_e32 v12, v13, v14
	v_min_f32_e32 v14, v13, v14
	v_max_f32_e32 v13, v11, v232
	v_min_f32_e32 v232, v11, v232
	v_max_f32_e32 v11, v2, v3
	v_min_f32_e32 v3, v2, v3
	v_max_f32_e32 v2, v5, v6
	v_min_f32_e32 v6, v5, v6
	v_max_f32_e32 v5, v4, v8
	v_min_f32_e32 v8, v4, v8
	v_max_f32_e32 v4, v7, v9
	v_min_f32_e32 v9, v7, v9
	v_max_f32_e32 v7, v10, v12
	v_min_f32_e32 v12, v10, v12
	v_max_f32_e32 v10, v14, v15
	v_min_f32_e32 v15, v14, v15
	v_max_f32_e32 v14, v16, v17
	v_min_f32_e32 v17, v16, v17
	v_max3_f32 v16, v13, v11, v231
	v_min_f32_e32 v11, v13, v11
	v_max_f32_e32 v13, v232, v3
	v_min_f32_e32 v3, v232, v3
	v_max_f32_e32 v231, v2, v7
	v_min_f32_e32 v7, v2, v7
	v_max_f32_e32 v2, v6, v12
	v_min_f32_e32 v12, v6, v12
	v_max_f32_e32 v6, v5, v4
	v_min_f32_e32 v4, v5, v4
	v_max_f32_e32 v5, v8, v9
	v_min_f32_e32 v9, v8, v9
	v_max_f32_e32 v8, v10, v14
	v_min_f32_e32 v14, v10, v14
	v_max_f32_e32 v10, v15, v17
	v_min_f32_e32 v17, v15, v17
	v_max_f32_e32 v15, v13, v11
	v_min_f32_e32 v11, v13, v11
	v_max_f32_e32 v13, v3, v8
	v_min_f32_e32 v8, v3, v8
	v_max_f32_e32 v3, v231, v6
	v_min_f32_e32 v6, v231, v6
	v_max_f32_e32 v231, v2, v4
	v_min_f32_e32 v4, v2, v4
	v_max_f32_e32 v2, v5, v7
	v_min_f32_e32 v7, v5, v7
	v_max_f32_e32 v5, v9, v12
	v_min_f32_e32 v12, v9, v12
	v_max_f32_e32 v9, v10, v14
	v_min_f32_e32 v14, v10, v14
	v_max3_f32 v10, v15, v3, v230
	v_min_f32_e32 v3, v15, v3
	v_max_f32_e32 v15, v11, v6
	v_min_f32_e32 v6, v11, v6
	v_max_f32_e32 v11, v231, v2
	v_min_f32_e32 v2, v231, v2
	v_max_f32_e32 v230, v4, v7
	v_min_f32_e32 v7, v4, v7
	v_max_f32_e32 v4, v5, v9
	v_min_f32_e32 v9, v5, v9
	v_max_f32_e32 v5, v12, v14
	v_min_f32_e32 v14, v12, v14
	v_max3_f32 v12, v15, v3, v229
	v_min_f32_e32 v3, v15, v3
	v_max_f32_e32 v15, v13, v6
	v_min_f32_e32 v6, v13, v6
	v_max_f32_e32 v13, v4, v8
	v_min_f32_e32 v8, v4, v8
	v_max_f32_e32 v4, v5, v9
	v_min_f32_e32 v9, v5, v9
	v_max_f32_e32 v5, v15, v11
	v_min_f32_e32 v11, v15, v11
	v_max_f32_e32 v15, v6, v2
	v_min_f32_e32 v2, v6, v2
	v_max_f32_e32 v6, v230, v13
	v_min_f32_e32 v13, v230, v13
	v_max_f32_e32 v229, v7, v8
	v_min_f32_e32 v8, v7, v8
	v_max3_f32 v7, v5, v3, v228
	v_min_f32_e32 v3, v5, v3
	v_max3_f32 v5, v11, v15, v207
	v_min_f32_e32 v15, v11, v15
	v_max_f32_e32 v11, v6, v2
	v_min_f32_e32 v2, v6, v2
	v_max_f32_e32 v6, v13, v229
	v_min_f32_e32 v229, v13, v229
	v_max3_f32 v13, v4, v8, v243
	v_min_f32_e32 v8, v4, v8
	v_max3_f32 v4, v15, v11, v206
	v_min_f32_e32 v11, v15, v11
	v_max3_f32 v15, v2, v6, v154
	v_min_f32_e32 v6, v2, v6
	v_max_f32_e32 v17, v239, v17
	v_max_f32_e32 v14, v240, v14
	v_max_f32_e32 v9, v241, v9
	v_max_f32_e32 v8, v242, v8
	v_max_f32_e32 v229, v252, v229
	v_max_f32_e32 v6, v253, v6
	v_max_f32_e32 v11, v205, v11
	v_max_f32_e32 v3, v227, v3
	v_max_f32_e32 v2, v16, v15
	v_min_f32_e32 v15, v16, v15
	v_max_f32_e32 v16, v10, v6
	v_min_f32_e32 v6, v10, v6
	v_max_f32_e32 v10, v12, v229
	v_min_f32_e32 v229, v12, v229
	v_max_f32_e32 v12, v7, v13
	v_min_f32_e32 v13, v7, v13
	v_max_f32_e32 v7, v3, v8
	v_min_f32_e32 v8, v3, v8
	v_max_f32_e32 v3, v5, v9
	v_min_f32_e32 v9, v5, v9
	v_max_f32_e32 v5, v4, v14
	v_min_f32_e32 v14, v4, v14
	v_max_f32_e32 v4, v11, v17
	v_min_f32_e32 v17, v11, v17
	v_max_f32_e32 v11, v2, v7
	v_min_f32_e32 v7, v2, v7
	v_max_f32_e32 v2, v16, v3
	v_min_f32_e32 v3, v16, v3
	v_max_f32_e32 v16, v10, v5
	v_min_f32_e32 v5, v10, v5
	v_max_f32_e32 v10, v12, v4
	v_min_f32_e32 v4, v12, v4
	v_max_f32_e32 v12, v15, v8
	v_min_f32_e32 v8, v15, v8
	v_max_f32_e32 v15, v6, v9
	v_min_f32_e32 v9, v6, v9
	v_max_f32_e32 v6, v229, v14
	v_min_f32_e32 v14, v229, v14
	v_max_f32_e32 v239, v13, v17
	v_min_f32_e32 v17, v13, v17
	v_max_f32_e32 v13, v11, v16
	v_min_f32_e32 v16, v11, v16
	v_max_f32_e32 v11, v2, v10
	v_min_f32_e32 v10, v2, v10
	v_max_f32_e32 v2, v7, v5
	v_min_f32_e32 v5, v7, v5
	v_max_f32_e32 v7, v3, v4
	v_min_f32_e32 v4, v3, v4
	v_max_f32_e32 v3, v12, v6
	v_min_f32_e32 v6, v12, v6
	v_max_f32_e32 v12, v15, v239
	v_min_f32_e32 v239, v15, v239
	v_max_f32_e32 v15, v8, v14
	v_min_f32_e32 v14, v8, v14
	v_max_f32_e32 v8, v9, v17
	v_min_f32_e32 v17, v9, v17
	v_max_f32_e32 v232, v13, v11
	v_min_f32_e32 v233, v13, v11
	v_max_f32_e32 v234, v16, v10
	v_min_f32_e32 v235, v16, v10
	v_max_f32_e32 v236, v2, v7
	v_min_f32_e32 v237, v2, v7
	v_max_f32_e32 v238, v5, v4
	v_min_f32_e32 v154, v5, v4
	v_max_f32_e32 v205, v3, v12
	v_min_f32_e32 v206, v3, v12
	v_max_f32_e32 v207, v6, v239
	v_min_f32_e32 v227, v6, v239
	v_max_f32_e32 v228, v15, v8
	v_min_f32_e32 v229, v15, v8
	v_max_f32_e32 v230, v14, v17
	v_min_f32_e32 v231, v14, v17
	s_waitcnt vmcnt(0)
	v_mfma_f32_32x32x16_bf16 v[2:17], v[244:247], v[46:49], 0
	v_mfma_f32_32x32x16_bf16 v[2:17], v[58:61], v[42:45], v[2:17]
	v_mfma_f32_32x32x16_bf16 v[2:17], v[54:57], v[38:41], v[2:17]
	v_mfma_f32_32x32x16_bf16 v[2:17], v[50:53], v[34:37], v[2:17]
	s_nop 11
	v_and_or_b32 v2, v2, s33, v189
	v_and_or_b32 v3, v3, s33, v190
	v_and_or_b32 v4, v4, s33, v191
	v_and_or_b32 v5, v5, s33, v192
	v_and_or_b32 v6, v6, s33, v193
	v_and_or_b32 v7, v7, s33, v194
	v_and_or_b32 v8, v8, s33, v195
	v_and_or_b32 v9, v9, s33, v196
	v_and_or_b32 v10, v10, s33, v197
	v_and_or_b32 v11, v11, s33, v198
	v_and_or_b32 v12, v12, s33, v199
	v_and_or_b32 v13, v13, s33, v200
	v_and_or_b32 v14, v14, s33, v201
	v_and_or_b32 v15, v15, s33, v202
	v_and_or_b32 v16, v16, s33, v203
	v_and_or_b32 v17, v17, s33, v204
	v_max_f32_e32 v35, v2, v15
	v_min_f32_e32 v15, v2, v15
	v_max_f32_e32 v36, v3, v14
	v_min_f32_e32 v14, v3, v14
	v_max_f32_e32 v37, v4, v17
	v_min_f32_e32 v17, v4, v17
	v_max_f32_e32 v38, v5, v16
	v_min_f32_e32 v16, v5, v16
	v_max_f32_e32 v39, v6, v10
	v_min_f32_e32 v10, v6, v10
	v_max_f32_e32 v40, v7, v8
	v_min_f32_e32 v8, v7, v8
	v_max_f32_e32 v41, v9, v13
	v_min_f32_e32 v13, v9, v13
	v_max_f32_e32 v42, v11, v12
	v_min_f32_e32 v12, v11, v12
	v_max_f32_e32 v43, v35, v40
	v_min_f32_e32 v40, v35, v40
	v_max_f32_e32 v35, v36, v41
	v_min_f32_e32 v41, v36, v41
	v_max_f32_e32 v36, v37, v42
	v_min_f32_e32 v42, v37, v42
	v_max_f32_e32 v37, v38, v39
	v_min_f32_e32 v39, v38, v39
	v_max_f32_e32 v38, v8, v15
	v_min_f32_e32 v15, v8, v15
	v_max_f32_e32 v44, v10, v16
	v_min_f32_e32 v16, v10, v16
	v_max_f32_e32 v45, v12, v17
	v_min_f32_e32 v17, v12, v17
	v_max_f32_e32 v46, v13, v14
	v_min_f32_e32 v14, v13, v14
	v_max_f32_e32 v47, v43, v35
	v_min_f32_e32 v35, v43, v35
	v_max_f32_e32 v43, v36, v37
	v_min_f32_e32 v37, v36, v37
	v_max_f32_e32 v36, v39, v40
	v_min_f32_e32 v40, v39, v40
	v_max_f32_e32 v39, v38, v44
	v_min_f32_e32 v44, v38, v44
	v_max_f32_e32 v38, v41, v42
	v_min_f32_e32 v42, v41, v42
	v_max_f32_e32 v41, v45, v46
	v_min_f32_e32 v46, v45, v46
	v_max_f32_e32 v45, v14, v15
	v_min_f32_e32 v15, v14, v15
	v_max_f32_e32 v48, v16, v17
	v_min_f32_e32 v17, v16, v17
	v_max3_f32 v2, v47, v43, v231
	v_min_f32_e32 v43, v47, v43
	v_max_f32_e32 v47, v35, v37
	v_min_f32_e32 v37, v35, v37
	v_max_f32_e32 v35, v36, v41
	v_min_f32_e32 v41, v36, v41
	v_max_f32_e32 v36, v40, v46
	v_min_f32_e32 v46, v40, v46
	v_max_f32_e32 v40, v39, v38
	v_min_f32_e32 v38, v39, v38
	v_max_f32_e32 v39, v44, v42
	v_min_f32_e32 v42, v44, v42
	v_max_f32_e32 v44, v45, v48
	v_min_f32_e32 v48, v45, v48
	v_max_f32_e32 v45, v15, v17
	v_min_f32_e32 v17, v15, v17
	v_max_f32_e32 v3, v47, v43
	v_min_f32_e32 v43, v47, v43
	v_max_f32_e32 v47, v37, v44
	v_min_f32_e32 v44, v37, v44
	v_max_f32_e32 v37, v35, v40
	v_min_f32_e32 v40, v35, v40
	v_max_f32_e32 v35, v36, v38
	v_min_f32_e32 v38, v36, v38
	v_max_f32_e32 v36, v39, v41
	v_min_f32_e32 v41, v39, v41
	v_max_f32_e32 v39, v42, v46
	v_min_f32_e32 v46, v42, v46
	v_max_f32_e32 v42, v45, v48
	v_min_f32_e32 v48, v45, v48
	v_max3_f32 v45, v3, v37, v230
	v_min_f32_e32 v37, v3, v37
	v_max_f32_e32 v3, v43, v40
	v_min_f32_e32 v40, v43, v40
	v_max_f32_e32 v43, v35, v36
	v_min_f32_e32 v36, v35, v36
	v_max_f32_e32 v35, v38, v41
	v_min_f32_e32 v41, v38, v41
	v_max_f32_e32 v38, v39, v42
	v_min_f32_e32 v42, v39, v42
	v_max_f32_e32 v39, v46, v48
	v_min_f32_e32 v48, v46, v48
	v_max3_f32 v46, v3, v37, v229
	v_min_f32_e32 v37, v3, v37
	v_max_f32_e32 v3, v47, v40
	v_min_f32_e32 v40, v47, v40
	v_max_f32_e32 v47, v38, v44
	v_min_f32_e32 v44, v38, v44
	v_max_f32_e32 v38, v39, v42
	v_min_f32_e32 v42, v39, v42
	v_max_f32_e32 v39, v3, v43
	v_min_f32_e32 v43, v3, v43
	v_max_f32_e32 v3, v40, v36
	v_min_f32_e32 v36, v40, v36
	v_max_f32_e32 v40, v35, v47
	v_min_f32_e32 v47, v35, v47
	v_max_f32_e32 v35, v41, v44
	v_min_f32_e32 v44, v41, v44
	v_max3_f32 v41, v39, v37, v228
	v_min_f32_e32 v37, v39, v37
	v_max3_f32 v39, v43, v3, v207
	v_min_f32_e32 v3, v43, v3
	v_max_f32_e32 v43, v40, v36
	v_min_f32_e32 v36, v40, v36
	v_max_f32_e32 v40, v47, v35
	v_min_f32_e32 v35, v47, v35
	v_max3_f32 v47, v38, v44, v236
	v_min_f32_e32 v44, v38, v44
	v_max3_f32 v38, v3, v43, v206
	v_min_f32_e32 v43, v3, v43
	v_max3_f32 v3, v36, v40, v154
	v_min_f32_e32 v40, v36, v40
	v_max_f32_e32 v17, v232, v17
	v_max_f32_e32 v48, v233, v48
	v_max_f32_e32 v42, v234, v42
	v_max_f32_e32 v44, v235, v44
	v_max_f32_e32 v35, v237, v35
	v_max_f32_e32 v40, v238, v40
	v_max_f32_e32 v43, v205, v43
	v_max_f32_e32 v37, v227, v37
	v_max_f32_e32 v36, v2, v3
	v_min_f32_e32 v3, v2, v3
	v_max_f32_e32 v2, v45, v40
	v_min_f32_e32 v40, v45, v40
	v_max_f32_e32 v45, v46, v35
	v_min_f32_e32 v35, v46, v35
	v_max_f32_e32 v46, v41, v47
	v_min_f32_e32 v47, v41, v47
	v_max_f32_e32 v41, v37, v44
	v_min_f32_e32 v44, v37, v44
	v_max_f32_e32 v37, v39, v42
	v_min_f32_e32 v42, v39, v42
	v_max_f32_e32 v39, v38, v48
	v_min_f32_e32 v48, v38, v48
	v_max_f32_e32 v38, v43, v17
	v_min_f32_e32 v17, v43, v17
	v_max_f32_e32 v43, v36, v41
	v_min_f32_e32 v41, v36, v41
	v_max_f32_e32 v36, v2, v37
	v_min_f32_e32 v37, v2, v37
	v_max_f32_e32 v2, v45, v39
	v_min_f32_e32 v39, v45, v39
	v_max_f32_e32 v45, v46, v38
	v_min_f32_e32 v38, v46, v38
	v_max_f32_e32 v46, v3, v44
	v_min_f32_e32 v44, v3, v44
	v_max_f32_e32 v3, v40, v42
	v_min_f32_e32 v42, v40, v42
	v_max_f32_e32 v40, v35, v48
	v_min_f32_e32 v48, v35, v48
	v_max_f32_e32 v35, v47, v17
	v_min_f32_e32 v17, v47, v17
	v_max_f32_e32 v47, v43, v2
	v_min_f32_e32 v2, v43, v2
	v_max_f32_e32 v43, v36, v45
	v_min_f32_e32 v45, v36, v45
	v_max_f32_e32 v36, v41, v39
	v_min_f32_e32 v39, v41, v39
	v_max_f32_e32 v41, v37, v38
	v_min_f32_e32 v38, v37, v38
	v_max_f32_e32 v37, v46, v40
	v_min_f32_e32 v40, v46, v40
	v_max_f32_e32 v46, v3, v35
	v_min_f32_e32 v35, v3, v35
	v_max_f32_e32 v3, v44, v48
	v_min_f32_e32 v48, v44, v48
	v_max_f32_e32 v44, v42, v17
	v_min_f32_e32 v17, v42, v17
	v_max_f32_e32 v15, v47, v43
	v_min_f32_e32 v43, v47, v43
	v_max_f32_e32 v12, v2, v45
	v_min_f32_e32 v5, v2, v45
	v_max_f32_e32 v9, v36, v41
	v_min_f32_e32 v41, v36, v41
	v_max_f32_e32 v34, v39, v38
	v_min_f32_e32 v4, v39, v38
	v_max_f32_e32 v11, v37, v46
	v_min_f32_e32 v13, v37, v46
	v_max_f32_e32 v16, v40, v35
	v_min_f32_e32 v7, v40, v35
	v_max_f32_e32 v14, v3, v44
	v_min_f32_e32 v8, v3, v44
	v_max_f32_e32 v10, v48, v17
	v_min_f32_e32 v2, v48, v17
	v_mov_b32_e32 v3, v43
	v_mov_b32_e32 v17, v41
	ds_bpermute_b32 v6, v121, v15
	ds_bpermute_b32 v35, v121, v3
	ds_bpermute_b32 v36, v121, v12
	ds_bpermute_b32 v37, v121, v5
	ds_bpermute_b32 v38, v121, v9
	ds_bpermute_b32 v39, v121, v17
	ds_bpermute_b32 v40, v121, v34
	ds_bpermute_b32 v41, v121, v4
	ds_bpermute_b32 v42, v121, v11
	ds_bpermute_b32 v43, v121, v13
	ds_bpermute_b32 v44, v121, v16
	ds_bpermute_b32 v45, v121, v7
	ds_bpermute_b32 v46, v121, v14
	ds_bpermute_b32 v47, v121, v8
	ds_bpermute_b32 v48, v121, v10
	ds_bpermute_b32 v49, v121, v2
	s_waitcnt lgkmcnt(4)
	s_waitcnt lgkmcnt(3)
	s_waitcnt lgkmcnt(2)
	s_waitcnt lgkmcnt(1)
	s_waitcnt lgkmcnt(0)
	v_max_f32_e32 v15, v15, v49
	v_max_f32_e32 v3, v3, v48
	v_max_f32_e32 v12, v12, v47
	v_max_f32_e32 v5, v5, v46
	v_max_f32_e32 v9, v9, v45
	v_max_f32_e32 v17, v17, v44
	v_max_f32_e32 v34, v34, v43
	v_max_f32_e32 v4, v4, v42
	v_max_f32_e32 v11, v11, v41
	v_max_f32_e32 v13, v13, v40
	v_max_f32_e32 v16, v16, v39
	v_max_f32_e32 v7, v7, v38
	v_max_f32_e32 v14, v14, v37
	v_max_f32_e32 v8, v8, v36
	v_max_f32_e32 v10, v10, v35
	v_max_f32_e32 v2, v2, v6
	v_max_f32_e32 v6, v15, v11
	v_min_f32_e32 v11, v15, v11
	v_max_f32_e32 v15, v3, v13
	v_min_f32_e32 v3, v3, v13
	v_max_f32_e32 v13, v12, v16
	v_min_f32_e32 v12, v12, v16
	v_max_f32_e32 v16, v5, v7
	v_min_f32_e32 v5, v5, v7
	v_max_f32_e32 v7, v9, v14
	v_min_f32_e32 v9, v9, v14
	v_max_f32_e32 v14, v17, v8
	v_min_f32_e32 v8, v17, v8
	v_max_f32_e32 v17, v34, v10
	v_min_f32_e32 v10, v34, v10
	v_max_f32_e32 v34, v4, v2
	v_min_f32_e32 v2, v4, v2
	v_max_f32_e32 v4, v6, v7
	v_min_f32_e32 v6, v6, v7
	v_max_f32_e32 v7, v15, v14
	v_min_f32_e32 v14, v15, v14
	v_max_f32_e32 v15, v13, v17
	v_min_f32_e32 v13, v13, v17
	v_max_f32_e32 v17, v16, v34
	v_min_f32_e32 v16, v16, v34
	v_max_f32_e32 v34, v11, v9
	v_min_f32_e32 v9, v11, v9
	v_max_f32_e32 v11, v3, v8
	v_min_f32_e32 v3, v3, v8
	v_max_f32_e32 v8, v12, v10
	v_min_f32_e32 v10, v12, v10
	v_max_f32_e32 v12, v5, v2
	v_max_f32_e32 v36, v34, v8
	v_min_f32_e32 v8, v34, v8
	v_max_f32_e32 v34, v11, v12
	v_min_f32_e32 v37, v11, v12
	v_max_f32_e32 v38, v9, v10
	v_min_f32_e32 v9, v9, v10
	v_max_f32_e32 v10, v36, v34
	v_min_f32_e32 v11, v36, v34
	v_mov_b32_e32 v34, v119
	v_min_f32_e32 v2, v5, v2
	v_max_f32_e32 v5, v4, v15
	v_min_f32_e32 v15, v4, v15
	v_max_f32_e32 v4, v7, v17
	v_min_f32_e32 v7, v7, v17
	v_max_f32_e32 v17, v6, v13
	v_min_f32_e32 v6, v6, v13
	v_max_f32_e32 v13, v14, v16
	v_min_f32_e32 v35, v14, v16
	v_max_f32_e32 v39, v3, v2
	v_min_f32_e32 v40, v3, v2
	v_and_b32_e32 v34, 31, v34
	v_max_f32_e32 v2, v5, v4
	v_min_f32_e32 v3, v5, v4
	v_max_f32_e32 v4, v15, v7
	v_min_f32_e32 v5, v15, v7
	v_max_f32_e32 v14, v17, v13
	v_min_f32_e32 v15, v17, v13
	v_max_f32_e32 v16, v6, v35
	v_min_f32_e32 v17, v6, v35
	v_max_f32_e32 v12, v8, v37
	v_min_f32_e32 v13, v8, v37
	v_max_f32_e32 v6, v38, v39
	v_min_f32_e32 v7, v38, v39
	v_max_f32_e32 v8, v9, v40
	v_min_f32_e32 v9, v9, v40
	v_lshl_add_u32 v36, v34, 7, s43
	s_lshl_b32 s10, s44, 10
	v_add_u32_e32 v36, s10, v36
	s_and_saveexec_b64 s[40:41], s[12:13]
	s_cbranch_execz .LBB0_24
	ds_write_b128 v36, v[30:33]
	ds_write_b128 v36, v[2:5] offset:64
	ds_write_b128 v36, v[26:29] offset:16
	ds_write_b128 v36, v[14:17] offset:80
	ds_write_b128 v36, v[22:25] offset:32
	ds_write_b128 v36, v[10:13] offset:96
	ds_write_b128 v36, v[18:21] offset:48
	ds_write_b128 v36, v[6:9] offset:112

.Ltk_merge:
	s_mov_b64 s[40:41], exec
	s_mov_b64 exec, s[12:13]
	v_mov_b32_e32 v2, v74
	v_mov_b32_e32 v3, v75
	v_mov_b32_e32 v4, v76
	v_mov_b32_e32 v5, v77
	v_mov_b32_e32 v6, v78
	v_mov_b32_e32 v7, v79
	v_mov_b32_e32 v8, v80
	v_mov_b32_e32 v9, v81
	v_mov_b32_e32 v10, v82
	v_mov_b32_e32 v11, v83
	v_mov_b32_e32 v12, v84
	v_mov_b32_e32 v13, v85
	v_mov_b32_e32 v14, v86
	v_mov_b32_e32 v15, v87
	v_mov_b32_e32 v16, v88
	v_mov_b32_e32 v17, v89
	v_mov_b32_e32 v18, v98
	v_mov_b32_e32 v19, v99
	v_mov_b32_e32 v20, v100
	v_mov_b32_e32 v21, v101
	v_mov_b32_e32 v22, v102
	v_mov_b32_e32 v23, v103
	v_mov_b32_e32 v24, v104
	v_mov_b32_e32 v25, v105
	v_mov_b32_e32 v26, v106
	v_mov_b32_e32 v27, v107
	v_mov_b32_e32 v28, v108
	v_mov_b32_e32 v29, v109
	v_mov_b32_e32 v30, v110
	v_mov_b32_e32 v31, v111
	v_mov_b32_e32 v32, v112
	v_mov_b32_e32 v33, v113
	v_add_u32_e32 v36, 0xffff8000, v36
	s_mov_b64 exec, s[40:41]
	v_and_b32_e32 v34, 63, v119
	v_and_b32_e32 v30, 0xffffff80, v30
	v_and_b32_e32 v31, 0xffffff80, v31
	v_and_b32_e32 v32, 0xffffff80, v32
	v_and_b32_e32 v33, 0xffffff80, v33
	v_and_b32_e32 v26, 0xffffff80, v26
	v_and_b32_e32 v27, 0xffffff80, v27
	v_and_b32_e32 v28, 0xffffff80, v28
	v_and_b32_e32 v29, 0xffffff80, v29
	v_and_b32_e32 v22, 0xffffff80, v22
	v_and_b32_e32 v23, 0xffffff80, v23
	v_and_b32_e32 v24, 0xffffff80, v24
	v_and_b32_e32 v25, 0xffffff80, v25
	v_and_b32_e32 v18, 0xffffff80, v18
	v_and_b32_e32 v19, 0xffffff80, v19
	v_and_b32_e32 v20, 0xffffff80, v20
	v_and_b32_e32 v21, 0xffffff80, v21
	v_and_b32_e32 v2, 0xffffff80, v2
	v_and_b32_e32 v3, 0xffffff80, v3
	v_and_b32_e32 v4, 0xffffff80, v4
	v_and_b32_e32 v5, 0xffffff80, v5
	v_and_b32_e32 v14, 0xffffff80, v14
	v_and_b32_e32 v15, 0xffffff80, v15
	v_and_b32_e32 v16, 0xffffff80, v16
	v_and_b32_e32 v17, 0xffffff80, v17
	v_and_b32_e32 v10, 0xffffff80, v10
	v_and_b32_e32 v11, 0xffffff80, v11
	v_and_b32_e32 v12, 0xffffff80, v12
	v_and_b32_e32 v13, 0xffffff80, v13
	v_and_b32_e32 v6, 0xffffff80, v6
	v_and_b32_e32 v7, 0xffffff80, v7
	v_and_b32_e32 v8, 0xffffff80, v8
	v_and_b32_e32 v9, 0xffffff80, v9
	v_add_f32_e32 v35, v30, v2
	v_and_or_b32 v35, v35, s78, 0
	v_add_f32_e32 v42, v30, v3
	v_and_or_b32 v42, v42, s78, 1
	v_add_f32_e32 v43, v30, v4
	v_and_or_b32 v43, v43, s78, 2
	v_add_f32_e32 v44, v30, v5
	v_and_or_b32 v44, v44, s78, 3
	v_add_f32_e32 v45, v30, v14
	v_and_or_b32 v45, v45, s78, 4
	v_add_f32_e32 v46, v30, v15
	v_and_or_b32 v46, v46, s78, 5
	v_add_f32_e32 v47, v30, v16
	v_and_or_b32 v47, v47, s78, 6
	v_add_f32_e32 v48, v30, v17
	v_and_or_b32 v48, v48, s78, 7
	v_add_f32_e32 v49, v30, v10
	v_and_or_b32 v49, v49, s78, 8
	v_add_f32_e32 v50, v30, v11
	v_and_or_b32 v50, v50, s78, 9
	v_add_f32_e32 v51, v30, v12
	v_and_or_b32 v51, v51, s78, 10
	v_add_f32_e32 v52, v30, v13
	v_and_or_b32 v52, v52, s78, 11
	v_add_f32_e32 v53, v30, v6
	v_and_or_b32 v53, v53, s78, 12
	v_add_f32_e32 v54, v30, v7
	v_and_or_b32 v54, v54, s78, 13
	v_add_f32_e32 v55, v30, v8
	v_and_or_b32 v55, v55, s78, 14
	v_add_f32_e32 v56, v30, v9
	v_and_or_b32 v56, v56, s78, 15
	v_add_f32_e32 v57, v31, v2
	v_and_or_b32 v57, v57, s78, 16
	v_add_f32_e32 v58, v31, v3
	v_and_or_b32 v58, v58, s78, 17
	v_add_f32_e32 v59, v31, v4
	v_and_or_b32 v59, v59, s78, 18
	v_add_f32_e32 v60, v31, v5
	v_and_or_b32 v60, v60, s78, 19
	v_add_f32_e32 v61, v31, v14
	v_and_or_b32 v61, v61, s78, 20
	v_add_f32_e32 v154, v31, v15
	v_and_or_b32 v154, v154, s78, 21
	v_add_f32_e32 v205, v31, v16
	v_and_or_b32 v205, v205, s78, 22
	v_add_f32_e32 v206, v31, v17
	v_and_or_b32 v206, v206, s78, 23
	v_max_f32_e32 v56, v56, v57
	v_max_f32_e32 v55, v55, v58
	v_max_f32_e32 v54, v54, v59
	v_max_f32_e32 v53, v53, v60
	v_max_f32_e32 v52, v52, v61
	v_max_f32_e32 v51, v51, v154
	v_max_f32_e32 v50, v50, v205
	v_max_f32_e32 v49, v49, v206
	v_max_f32_e32 v207, v35, v49
	v_min_f32_e32 v49, v35, v49
	v_max_f32_e32 v227, v42, v50
	v_min_f32_e32 v50, v42, v50
	v_max_f32_e32 v228, v43, v51
	v_min_f32_e32 v51, v43, v51
	v_max_f32_e32 v229, v44, v52
	v_min_f32_e32 v52, v44, v52
	v_max_f32_e32 v230, v45, v53
	v_min_f32_e32 v53, v45, v53
	v_max_f32_e32 v231, v46, v54
	v_min_f32_e32 v54, v46, v54
	v_max_f32_e32 v232, v47, v55
	v_min_f32_e32 v55, v47, v55
	v_max_f32_e32 v57, v48, v56
	v_min_f32_e32 v56, v48, v56
	v_max_f32_e32 v58, v207, v230
	v_min_f32_e32 v230, v207, v230
	v_max_f32_e32 v59, v227, v231
	v_min_f32_e32 v231, v227, v231
	v_max_f32_e32 v60, v228, v232
	v_min_f32_e32 v232, v228, v232
	v_max_f32_e32 v61, v229, v57
	v_min_f32_e32 v57, v229, v57
	v_max_f32_e32 v154, v49, v53
	v_min_f32_e32 v53, v49, v53
	v_max_f32_e32 v205, v50, v54
	v_min_f32_e32 v54, v50, v54
	v_max_f32_e32 v206, v51, v55
	v_min_f32_e32 v55, v51, v55
	v_max_f32_e32 v35, v52, v56
	v_min_f32_e32 v56, v52, v56
	v_max_f32_e32 v42, v58, v60
	v_min_f32_e32 v60, v58, v60
	v_max_f32_e32 v43, v59, v61
	v_min_f32_e32 v61, v59, v61
	v_max_f32_e32 v44, v230, v232
	v_min_f32_e32 v232, v230, v232
	v_max_f32_e32 v45, v231, v57
	v_min_f32_e32 v57, v231, v57
	v_max_f32_e32 v46, v154, v206
	v_min_f32_e32 v206, v154, v206
	v_max_f32_e32 v47, v205, v35
	v_min_f32_e32 v35, v205, v35
	v_max_f32_e32 v48, v53, v55
	v_min_f32_e32 v55, v53, v55
	v_max_f32_e32 v207, v54, v56
	v_min_f32_e32 v56, v54, v56
	v_max_f32_e32 v227, v42, v43
	v_min_f32_e32 v43, v42, v43
	v_max_f32_e32 v228, v60, v61
	v_min_f32_e32 v61, v60, v61
	v_max_f32_e32 v229, v44, v45
	v_min_f32_e32 v45, v44, v45
	v_max_f32_e32 v49, v232, v57
	v_min_f32_e32 v57, v232, v57
	v_max_f32_e32 v50, v46, v47
	v_min_f32_e32 v47, v46, v47
	v_max_f32_e32 v51, v206, v35
	v_min_f32_e32 v35, v206, v35
	v_max_f32_e32 v52, v48, v207
	v_min_f32_e32 v207, v48, v207
	v_max_f32_e32 v58, v55, v56
	v_min_f32_e32 v56, v55, v56
	v_add_f32_e32 v59, v32, v2
	v_and_or_b32 v59, v59, s78, 32
	v_add_f32_e32 v230, v32, v3
	v_and_or_b32 v230, v230, s78, 33
	v_add_f32_e32 v231, v32, v4
	v_and_or_b32 v231, v231, s78, 34
	v_add_f32_e32 v154, v32, v5
	v_and_or_b32 v154, v154, s78, 35
	v_add_f32_e32 v205, v32, v14
	v_and_or_b32 v205, v205, s78, 36
	v_max_f32_e32 v56, v56, v59
	v_max_f32_e32 v58, v58, v230
	v_max_f32_e32 v207, v207, v231
	v_max_f32_e32 v52, v52, v154
	v_max_f32_e32 v35, v35, v205
	v_max_f32_e32 v53, v227, v50
	v_min_f32_e32 v50, v227, v50
	v_max_f32_e32 v54, v43, v47
	v_min_f32_e32 v47, v43, v47
	v_max_f32_e32 v42, v228, v51
	v_min_f32_e32 v51, v228, v51
	v_max_f32_e32 v60, v61, v35
	v_min_f32_e32 v35, v61, v35
	v_max_f32_e32 v44, v229, v52
	v_min_f32_e32 v52, v229, v52
	v_max_f32_e32 v232, v45, v207
	v_min_f32_e32 v207, v45, v207
	v_max_f32_e32 v46, v49, v58
	v_min_f32_e32 v58, v49, v58
	v_max_f32_e32 v206, v57, v56
	v_min_f32_e32 v56, v57, v56
	v_max_f32_e32 v48, v53, v44
	v_min_f32_e32 v44, v53, v44
	v_max_f32_e32 v55, v54, v232
	v_min_f32_e32 v232, v54, v232
	v_max_f32_e32 v59, v42, v46
	v_min_f32_e32 v46, v42, v46
	v_max_f32_e32 v230, v60, v206
	v_min_f32_e32 v206, v60, v206
	v_max_f32_e32 v231, v50, v52
	v_min_f32_e32 v52, v50, v52
	v_max_f32_e32 v154, v47, v207
	v_min_f32_e32 v207, v47, v207
	v_max_f32_e32 v205, v51, v58
	v_min_f32_e32 v58, v51, v58
	v_max_f32_e32 v227, v35, v56
	v_min_f32_e32 v56, v35, v56
	v_max_f32_e32 v43, v48, v59
	v_min_f32_e32 v59, v48, v59
	v_max_f32_e32 v228, v55, v230
	v_min_f32_e32 v230, v55, v230
	v_max_f32_e32 v61, v44, v46
	v_min_f32_e32 v46, v44, v46
	v_max_f32_e32 v229, v232, v206
	v_min_f32_e32 v206, v232, v206
	v_max_f32_e32 v45, v231, v205
	v_min_f32_e32 v205, v231, v205
	v_max_f32_e32 v49, v154, v227
	v_min_f32_e32 v227, v154, v227
	v_max_f32_e32 v57, v52, v58
	v_min_f32_e32 v58, v52, v58
	v_max_f32_e32 v53, v207, v56
	v_min_f32_e32 v56, v207, v56
	v_max_f32_e32 v54, v43, v228
	v_min_f32_e32 v228, v43, v228
	v_max_f32_e32 v42, v59, v230
	v_min_f32_e32 v230, v59, v230
	v_max_f32_e32 v60, v61, v229
	v_min_f32_e32 v229, v61, v229
	v_max_f32_e32 v50, v46, v206
	v_min_f32_e32 v206, v46, v206
	v_max_f32_e32 v47, v45, v49
	v_min_f32_e32 v49, v45, v49
	v_max_f32_e32 v51, v205, v227
	v_min_f32_e32 v227, v205, v227
	v_max_f32_e32 v35, v57, v53
	v_min_f32_e32 v53, v57, v53
	v_max_f32_e32 v48, v58, v56
	v_min_f32_e32 v56, v58, v56
	v_add_f32_e32 v55, v33, v2
	v_and_or_b32 v55, v55, s78, 48
	v_add_f32_e32 v44, v33, v3
	v_and_or_b32 v44, v44, s78, 49
	v_add_f32_e32 v232, v33, v4
	v_and_or_b32 v232, v232, s78, 50
	v_add_f32_e32 v231, v33, v5
	v_and_or_b32 v231, v231, s78, 51
	v_max_f32_e32 v56, v56, v55
	v_max_f32_e32 v48, v48, v44
	v_max_f32_e32 v53, v53, v232
	v_max_f32_e32 v35, v35, v231
	v_max_f32_e32 v154, v54, v47
	v_min_f32_e32 v47, v54, v47
	v_max_f32_e32 v52, v228, v49
	v_min_f32_e32 v49, v228, v49
	v_max_f32_e32 v207, v42, v51
	v_min_f32_e32 v51, v42, v51
	v_max_f32_e32 v43, v230, v227
	v_min_f32_e32 v227, v230, v227
	v_max_f32_e32 v59, v60, v35
	v_min_f32_e32 v35, v60, v35
	v_max_f32_e32 v61, v229, v53
	v_min_f32_e32 v53, v229, v53
	v_max_f32_e32 v46, v50, v48
	v_min_f32_e32 v48, v50, v48
	v_max_f32_e32 v45, v206, v56
	v_min_f32_e32 v56, v206, v56
	v_max_f32_e32 v205, v154, v59
	v_min_f32_e32 v59, v154, v59
	v_max_f32_e32 v57, v52, v61
	v_min_f32_e32 v61, v52, v61
	v_max_f32_e32 v58, v207, v46
	v_min_f32_e32 v46, v207, v46
	v_max_f32_e32 v55, v43, v45
	v_min_f32_e32 v45, v43, v45
	v_max_f32_e32 v44, v47, v35
	v_min_f32_e32 v35, v47, v35
	v_max_f32_e32 v232, v49, v53
	v_min_f32_e32 v53, v49, v53
	v_max_f32_e32 v231, v51, v48
	v_min_f32_e32 v48, v51, v48
	v_max_f32_e32 v54, v227, v56
	v_min_f32_e32 v56, v227, v56
	v_max_f32_e32 v228, v205, v58
	v_min_f32_e32 v58, v205, v58
	v_max_f32_e32 v42, v57, v55
	v_min_f32_e32 v55, v57, v55
	v_max_f32_e32 v230, v59, v46
	v_min_f32_e32 v46, v59, v46
	v_max_f32_e32 v60, v61, v45
	v_min_f32_e32 v45, v61, v45
	v_max_f32_e32 v229, v44, v231
	v_min_f32_e32 v231, v44, v231
	v_max_f32_e32 v50, v232, v54
	v_min_f32_e32 v54, v232, v54
	v_max_f32_e32 v206, v35, v48
	v_min_f32_e32 v48, v35, v48
	v_max_f32_e32 v154, v53, v56
	v_min_f32_e32 v56, v53, v56
	v_max_f32_e32 v52, v228, v42
	v_min_f32_e32 v42, v228, v42
	v_max_f32_e32 v207, v58, v55
	v_min_f32_e32 v55, v58, v55
	v_max_f32_e32 v43, v230, v60
	v_min_f32_e32 v60, v230, v60
	v_max_f32_e32 v47, v46, v45
	v_min_f32_e32 v45, v46, v45
	v_max_f32_e32 v49, v229, v50
	v_min_f32_e32 v50, v229, v50
	v_max_f32_e32 v51, v231, v54
	v_min_f32_e32 v54, v231, v54
	v_max_f32_e32 v227, v206, v154
	v_min_f32_e32 v154, v206, v154
	v_max_f32_e32 v205, v48, v56
	v_min_f32_e32 v56, v48, v56
	v_add_f32_e32 v57, v26, v2
	v_and_or_b32 v57, v57, s78, 64
	v_add_f32_e32 v59, v26, v3
	v_and_b32_e32 v59, s78, v59
	v_or_b32_e32 v59, 0x41, v59
	v_add_f32_e32 v61, v26, v4
	v_and_b32_e32 v61, s78, v61
	v_or_b32_e32 v61, 0x42, v61
	v_max_f32_e32 v56, v56, v57
	v_max_f32_e32 v205, v205, v59
	v_max_f32_e32 v154, v154, v61
	v_max_f32_e32 v44, v52, v49
	v_min_f32_e32 v49, v52, v49
	v_max_f32_e32 v232, v42, v50
	v_min_f32_e32 v50, v42, v50
	v_max_f32_e32 v35, v207, v51
	v_min_f32_e32 v51, v207, v51
	v_max_f32_e32 v53, v55, v54
	v_min_f32_e32 v54, v55, v54
	v_max_f32_e32 v228, v43, v227
	v_min_f32_e32 v227, v43, v227
	v_max_f32_e32 v58, v60, v154
	v_min_f32_e32 v154, v60, v154
	v_max_f32_e32 v230, v47, v205
	v_min_f32_e32 v205, v47, v205
	v_max_f32_e32 v46, v45, v56
	v_min_f32_e32 v56, v45, v56
	v_max_f32_e32 v229, v44, v228
	v_min_f32_e32 v228, v44, v228
	v_max_f32_e32 v231, v232, v58
	v_min_f32_e32 v58, v232, v58
	v_max_f32_e32 v206, v35, v230
	v_min_f32_e32 v230, v35, v230
	v_max_f32_e32 v48, v53, v46
	v_min_f32_e32 v46, v53, v46
	v_max_f32_e32 v57, v49, v227
	v_min_f32_e32 v227, v49, v227
	v_max_f32_e32 v59, v50, v154
	v_min_f32_e32 v154, v50, v154
	v_max_f32_e32 v61, v51, v205
	v_min_f32_e32 v205, v51, v205
	v_max_f32_e32 v52, v54, v56
	v_min_f32_e32 v56, v54, v56
	v_max_f32_e32 v42, v229, v206
	v_min_f32_e32 v206, v229, v206
	v_max_f32_e32 v207, v231, v48
	v_min_f32_e32 v48, v231, v48
	v_max_f32_e32 v55, v228, v230
	v_min_f32_e32 v230, v228, v230
	v_max_f32_e32 v43, v58, v46
	v_min_f32_e32 v46, v58, v46
	v_max_f32_e32 v60, v57, v61
	v_min_f32_e32 v61, v57, v61
	v_max_f32_e32 v47, v59, v52
	v_min_f32_e32 v52, v59, v52
	v_max_f32_e32 v45, v227, v205
	v_min_f32_e32 v205, v227, v205
	v_max_f32_e32 v44, v154, v56
	v_min_f32_e32 v56, v154, v56
	v_max_f32_e32 v232, v42, v207
	v_min_f32_e32 v207, v42, v207
	v_max_f32_e32 v35, v206, v48
	v_min_f32_e32 v48, v206, v48
	v_max_f32_e32 v53, v55, v43
	v_min_f32_e32 v43, v55, v43
	v_max_f32_e32 v49, v230, v46
	v_min_f32_e32 v46, v230, v46
	v_max_f32_e32 v50, v60, v47
	v_min_f32_e32 v47, v60, v47
	v_max_f32_e32 v51, v61, v52
	v_min_f32_e32 v52, v61, v52
	v_max_f32_e32 v54, v45, v44
	v_min_f32_e32 v44, v45, v44
	v_max_f32_e32 v229, v205, v56
	v_min_f32_e32 v56, v205, v56
	v_add_f32_e32 v231, v27, v2
	v_and_b32_e32 v231, s78, v231
	v_or_b32_e32 v231, 0x50, v231
	v_add_f32_e32 v228, v28, v2
	v_and_b32_e32 v228, s78, v228
	v_or_b32_e32 v228, 0x60, v228
	v_add_f32_e32 v58, v29, v2
	v_and_b32_e32 v58, s78, v58
	v_or_b32_e32 v58, 0x70, v58
	v_add_f32_e32 v57, v22, v2
	v_and_b32_e32 v57, s78, v57
	v_or_b32_e32 v57, 0x80, v57
	v_add_f32_e32 v59, v23, v2
	v_and_b32_e32 v59, s78, v59
	v_or_b32_e32 v59, 0x90, v59
	v_add_f32_e32 v227, v24, v2
	v_and_b32_e32 v227, s78, v227
	v_or_b32_e32 v227, 0xa0, v227
	v_add_f32_e32 v154, v25, v2
	v_and_b32_e32 v154, s78, v154
	v_or_b32_e32 v154, 0xb0, v154
	v_add_f32_e32 v42, v18, v2
	v_and_b32_e32 v42, s78, v42
	v_or_b32_e32 v42, 0xc0, v42
	v_add_f32_e32 v206, v19, v2
	v_and_b32_e32 v206, s78, v206
	v_or_b32_e32 v206, 0xd0, v206
	v_add_f32_e32 v55, v20, v2
	v_and_b32_e32 v55, s78, v55
	v_or_b32_e32 v55, 0xe0, v55
	v_add_f32_e32 v230, v21, v2
	v_and_b32_e32 v230, s78, v230
	v_or_b32_e32 v230, 0xf0, v230
	v_max_f32_e32 v56, v56, v231
	v_max_f32_e32 v229, v229, v228
	v_max_f32_e32 v44, v44, v58
	v_max_f32_e32 v54, v54, v57
	v_max_f32_e32 v52, v52, v59
	v_max_f32_e32 v51, v51, v227
	v_max_f32_e32 v47, v47, v154
	v_max_f32_e32 v50, v50, v42
	v_max_f32_e32 v46, v46, v206
	v_max_f32_e32 v49, v49, v55
	v_max_f32_e32 v43, v43, v230
	v_max_f32_e32 v60, v232, v50
	v_min_f32_e32 v50, v232, v50
	v_max_f32_e32 v61, v207, v47
	v_min_f32_e32 v47, v207, v47
	v_max_f32_e32 v45, v35, v51
	v_min_f32_e32 v51, v35, v51
	v_max_f32_e32 v205, v48, v52
	v_min_f32_e32 v52, v48, v52
	v_max_f32_e32 v231, v53, v54
	v_min_f32_e32 v54, v53, v54
	v_max_f32_e32 v228, v43, v44
	v_min_f32_e32 v44, v43, v44
	v_max_f32_e32 v58, v49, v229
	v_min_f32_e32 v229, v49, v229
	v_max_f32_e32 v57, v46, v56
	v_min_f32_e32 v56, v46, v56
	v_max_f32_e32 v59, v60, v231
	v_min_f32_e32 v231, v60, v231
	v_max_f32_e32 v227, v61, v228
	v_min_f32_e32 v228, v61, v228
	v_max_f32_e32 v154, v45, v58
	v_min_f32_e32 v58, v45, v58
	v_max_f32_e32 v42, v205, v57
	v_min_f32_e32 v57, v205, v57
	v_max_f32_e32 v206, v50, v54
	v_min_f32_e32 v54, v50, v54
	v_max_f32_e32 v55, v47, v44
	v_min_f32_e32 v44, v47, v44
	v_max_f32_e32 v230, v51, v229
	v_min_f32_e32 v229, v51, v229
	v_max_f32_e32 v232, v52, v56
	v_min_f32_e32 v56, v52, v56
	v_max_f32_e32 v207, v59, v154
	v_min_f32_e32 v154, v59, v154
	v_max_f32_e32 v35, v227, v42
	v_min_f32_e32 v42, v227, v42
	v_max_f32_e32 v48, v231, v58
	v_min_f32_e32 v58, v231, v58
	v_max_f32_e32 v53, v228, v57
	v_min_f32_e32 v57, v228, v57
	v_max_f32_e32 v43, v206, v230
	v_min_f32_e32 v230, v206, v230
	v_max_f32_e32 v49, v55, v232
	v_min_f32_e32 v232, v55, v232
	v_max_f32_e32 v46, v54, v229
	v_min_f32_e32 v229, v54, v229
	v_max_f32_e32 v60, v44, v56
	v_min_f32_e32 v56, v44, v56
	v_max_f32_e32 v61, v207, v35
	v_min_f32_e32 v35, v207, v35
	v_max_f32_e32 v45, v154, v42
	v_min_f32_e32 v42, v154, v42
	v_max_f32_e32 v205, v48, v53
	v_min_f32_e32 v53, v48, v53
	v_max_f32_e32 v50, v58, v57
	v_min_f32_e32 v57, v58, v57
	v_max_f32_e32 v47, v43, v49
	v_min_f32_e32 v49, v43, v49
	v_max_f32_e32 v51, v230, v232
	v_min_f32_e32 v232, v230, v232
	v_max_f32_e32 v52, v46, v60
	v_min_f32_e32 v60, v46, v60
	v_max_f32_e32 v59, v229, v56
	v_min_f32_e32 v56, v229, v56
	v_add_f32_e32 v227, v27, v3
	v_and_b32_e32 v227, s78, v227
	v_or_b32_e32 v227, 0x51, v227
	v_add_f32_e32 v231, v28, v3
	v_and_b32_e32 v231, s78, v231
	v_or_b32_e32 v231, 0x61, v231
	v_add_f32_e32 v228, v29, v3
	v_and_b32_e32 v228, s78, v228
	v_or_b32_e32 v228, 0x71, v228
	v_max_f32_e32 v56, v56, v227
	v_max_f32_e32 v59, v59, v231
	v_max_f32_e32 v60, v60, v228
	v_max_f32_e32 v206, v61, v47
	v_min_f32_e32 v47, v61, v47
	v_max_f32_e32 v55, v35, v49
	v_min_f32_e32 v49, v35, v49
	v_max_f32_e32 v54, v45, v51
	v_min_f32_e32 v51, v45, v51
	v_max_f32_e32 v44, v42, v232
	v_min_f32_e32 v232, v42, v232
	v_max_f32_e32 v207, v205, v52
	v_min_f32_e32 v52, v205, v52
	v_max_f32_e32 v154, v53, v60
	v_min_f32_e32 v60, v53, v60
	v_max_f32_e32 v48, v50, v59
	v_min_f32_e32 v59, v50, v59
	v_max_f32_e32 v58, v57, v56
	v_min_f32_e32 v56, v57, v56
	v_max_f32_e32 v43, v206, v207
	v_min_f32_e32 v207, v206, v207
	v_max_f32_e32 v230, v55, v154
	v_min_f32_e32 v154, v55, v154
	v_max_f32_e32 v46, v54, v48
	v_min_f32_e32 v48, v54, v48
	v_max_f32_e32 v229, v44, v58
	v_min_f32_e32 v58, v44, v58
	v_max_f32_e32 v227, v47, v52
	v_min_f32_e32 v52, v47, v52
	v_max_f32_e32 v231, v49, v60
	v_min_f32_e32 v60, v49, v60
	v_max_f32_e32 v228, v51, v59
	v_min_f32_e32 v59, v51, v59
	v_max_f32_e32 v61, v232, v56
	v_min_f32_e32 v56, v232, v56
	v_max_f32_e32 v35, v43, v46
	v_min_f32_e32 v46, v43, v46
	v_max_f32_e32 v45, v230, v229
	v_min_f32_e32 v229, v230, v229
	v_max_f32_e32 v42, v207, v48
	v_min_f32_e32 v48, v207, v48
	v_max_f32_e32 v205, v154, v58
	v_min_f32_e32 v58, v154, v58
	v_max_f32_e32 v53, v227, v228
	v_min_f32_e32 v228, v227, v228
	v_max_f32_e32 v50, v231, v61
	v_min_f32_e32 v61, v231, v61
	v_max_f32_e32 v57, v52, v59
	v_min_f32_e32 v59, v52, v59
	v_max_f32_e32 v206, v60, v56
	v_min_f32_e32 v56, v60, v56
	v_max_f32_e32 v41, v35, v45
	v_min_f32_e32 v40, v35, v45
	v_max_f32_e32 v39, v46, v229
	v_min_f32_e32 v38, v46, v229
	v_max_f32_e32 v37, v42, v205
	v_min_f32_e32 v33, v42, v205
	v_max_f32_e32 v32, v48, v58
	v_min_f32_e32 v31, v48, v58
	v_max_f32_e32 v30, v53, v50
	v_min_f32_e32 v29, v53, v50
	v_max_f32_e32 v28, v228, v61
	v_min_f32_e32 v27, v228, v61
	v_max_f32_e32 v26, v57, v206
	v_min_f32_e32 v25, v57, v206
	v_max_f32_e32 v24, v59, v56
	v_min_f32_e32 v19, v59, v56
	v_and_b32_e32 v17, 0xffffff00, v41
	v_sub_f32_e32 v2, v17, v17
	v_mul_f32_e32 v6, 0x3fb8aa3b, v2
	v_fma_f32 v7, v2, s79, -v6
	v_rndne_f32_e32 v22, v6
	v_fmac_f32_e32 v7, 0x32a5705f, v2
	v_sub_f32_e32 v6, v6, v22
	v_add_f32_e32 v6, v6, v7
	v_exp_f32_e32 v6, v6
	v_cvt_i32_f32_e32 v7, v22
	v_and_b32_e32 v3, 0xffffff00, v40
	v_cmp_ngt_f32_e32 vcc, s80, v2
	v_sub_f32_e32 v3, v3, v17
	v_ldexp_f32 v6, v6, v7
	v_cndmask_b32_e32 v6, 0, v6, vcc
	v_and_b32_e32 v4, 0xffffff00, v39
	v_sub_f32_e32 v4, v4, v17
	v_mov_b32_e32 v2, v6
	v_mul_f32_e32 v6, 0x3fb8aa3b, v3
	v_fma_f32 v7, v3, s79, -v6
	v_rndne_f32_e32 v22, v6
	v_fmac_f32_e32 v7, 0x32a5705f, v3
	v_sub_f32_e32 v6, v6, v22
	v_add_f32_e32 v6, v6, v7
	v_exp_f32_e32 v6, v6
	v_cvt_i32_f32_e32 v7, v22
	v_cmp_ngt_f32_e32 vcc, s80, v3
	v_and_b32_e32 v5, 0xffffff00, v38
	v_sub_f32_e32 v5, v5, v17
	v_ldexp_f32 v6, v6, v7
	v_cndmask_b32_e32 v6, 0, v6, vcc
	v_and_b32_e32 v8, 0xffffff00, v37
	v_and_b32_e32 v9, 0xffffff00, v33
	v_mov_b32_e32 v3, v6
	v_mul_f32_e32 v6, 0x3fb8aa3b, v4
	v_fma_f32 v22, v4, s79, -v6
	v_rndne_f32_e32 v23, v6
	v_fmac_f32_e32 v22, 0x32a5705f, v4
	v_sub_f32_e32 v6, v6, v23
	v_add_f32_e32 v6, v6, v22
	v_exp_f32_e32 v6, v6
	v_cvt_i32_f32_e32 v22, v23
	v_cmp_ngt_f32_e32 vcc, s80, v4
	v_add_f32_e32 v7, v2, v3
	v_and_b32_e32 v10, 0xffffff00, v32
	v_ldexp_f32 v6, v6, v22
	v_cndmask_b32_e32 v6, 0, v6, vcc
	v_and_b32_e32 v11, 0xffffff00, v31
	v_and_b32_e32 v12, 0xffffff00, v30
	v_add_f32_e32 v4, v7, v6
	v_mul_f32_e32 v7, 0x3fb8aa3b, v5
	v_fma_f32 v22, v5, s79, -v7
	v_rndne_f32_e32 v23, v7
	v_fmac_f32_e32 v22, 0x32a5705f, v5
	v_sub_f32_e32 v7, v7, v23
	v_add_f32_e32 v7, v7, v22
	v_exp_f32_e32 v7, v7
	v_cvt_i32_f32_e32 v22, v23
	v_cmp_ngt_f32_e32 vcc, s80, v5
	v_and_b32_e32 v14, 0xffffff00, v29
	v_and_b32_e32 v15, 0xffffff00, v28
	v_ldexp_f32 v7, v7, v22
	v_cndmask_b32_e32 v7, 0, v7, vcc
	v_and_b32_e32 v20, 0xffffff00, v27
	v_and_b32_e32 v21, 0xffffff00, v26
	v_add_f32_e32 v5, v4, v7
	v_sub_f32_e32 v4, v8, v17
	v_mul_f32_e32 v8, 0x3fb8aa3b, v4
	v_fma_f32 v22, v4, s79, -v8
	v_rndne_f32_e32 v23, v8
	v_fmac_f32_e32 v22, 0x32a5705f, v4
	v_sub_f32_e32 v8, v8, v23
	v_add_f32_e32 v8, v8, v22
	v_exp_f32_e32 v8, v8
	v_cvt_i32_f32_e32 v22, v23
	v_cmp_ngt_f32_e32 vcc, s80, v4
	v_and_b32_e32 v13, 0xffffff00, v25
	v_sub_f32_e32 v13, v13, v17
	v_ldexp_f32 v8, v8, v22
	v_cndmask_b32_e32 v8, 0, v8, vcc
	v_and_b32_e32 v16, 0xffffff00, v24
	v_sub_f32_e32 v16, v16, v17
	v_mov_b32_e32 v4, v8
	v_add_f32_e32 v8, v5, v4
	v_sub_f32_e32 v5, v9, v17
	v_mul_f32_e32 v9, 0x3fb8aa3b, v5
	v_fma_f32 v22, v5, s79, -v9
	v_rndne_f32_e32 v23, v9
	v_fmac_f32_e32 v22, 0x32a5705f, v5
	v_sub_f32_e32 v9, v9, v23
	v_add_f32_e32 v9, v9, v22
	v_exp_f32_e32 v9, v9
	v_cvt_i32_f32_e32 v22, v23
	v_cmp_ngt_f32_e32 vcc, s80, v5
	v_and_b32_e32 v18, 0xffffff00, v19
	s_mov_b32 s10, s42
	v_ldexp_f32 v9, v9, v22
	v_cndmask_b32_e32 v9, 0, v9, vcc
	v_or_b32_e32 v34, s10, v34
	v_lshrrev_b32_e32 v42, 2, v39
	v_mov_b32_e32 v5, v9
	v_sub_f32_e32 v9, v10, v17
	v_mul_f32_e32 v10, 0x3fb8aa3b, v9
	v_fma_f32 v22, v9, s79, -v10
	v_rndne_f32_e32 v23, v10
	v_fmac_f32_e32 v22, 0x32a5705f, v9
	v_sub_f32_e32 v10, v10, v23
	v_add_f32_e32 v10, v10, v22
	v_exp_f32_e32 v10, v10
	v_cvt_i32_f32_e32 v22, v23
	v_cmp_ngt_f32_e32 vcc, s80, v9
	v_add_f32_e32 v8, v8, v5
	v_and_b32_e32 v39, 15, v39
	v_ldexp_f32 v10, v10, v22
	v_cndmask_b32_e32 v10, 0, v10, vcc
	v_sub_f32_e32 v9, v11, v17
	v_mul_f32_e32 v11, 0x3fb8aa3b, v9
	v_fma_f32 v22, v9, s79, -v11
	v_rndne_f32_e32 v23, v11
	v_fmac_f32_e32 v22, 0x32a5705f, v9
	v_sub_f32_e32 v11, v11, v23
	v_add_f32_e32 v11, v11, v22
	v_exp_f32_e32 v11, v11
	v_cvt_i32_f32_e32 v22, v23
	v_cmp_ngt_f32_e32 vcc, s80, v9
	v_add_f32_e32 v8, v8, v10
	v_ldexp_f32 v11, v11, v22
	v_cndmask_b32_e32 v11, 0, v11, vcc
	v_lshl_add_u32 v39, v39, 2, v36
	ds_read_b32 v43, v39 offset:64
	v_add_f32_e32 v9, v8, v11
	v_sub_f32_e32 v8, v12, v17
	v_mul_f32_e32 v12, 0x3fb8aa3b, v8
	v_fma_f32 v22, v8, s79, -v12
	v_rndne_f32_e32 v23, v12
	v_fmac_f32_e32 v22, 0x32a5705f, v8
	v_sub_f32_e32 v12, v12, v23
	v_add_f32_e32 v12, v12, v22
	v_exp_f32_e32 v12, v12
	v_cvt_i32_f32_e32 v22, v23
	v_cmp_ngt_f32_e32 vcc, s80, v8
	v_lshrrev_b32_e32 v39, 2, v38
	v_and_b32_e32 v42, 60, v42
	v_ldexp_f32 v12, v12, v22
	v_cndmask_b32_e32 v12, 0, v12, vcc
	v_and_b32_e32 v39, 60, v39
	v_add_u32_e32 v42, v36, v42
	v_mov_b32_e32 v8, v12
	v_add_f32_e32 v12, v9, v8
	v_sub_f32_e32 v9, v14, v17
	v_mul_f32_e32 v14, 0x3fb8aa3b, v9
	v_fma_f32 v22, v9, s79, -v14
	v_rndne_f32_e32 v23, v14
	v_fmac_f32_e32 v22, 0x32a5705f, v9
	v_sub_f32_e32 v14, v14, v23
	v_add_f32_e32 v14, v14, v22
	v_exp_f32_e32 v14, v14
	v_cvt_i32_f32_e32 v22, v23
	v_cmp_ngt_f32_e32 vcc, s80, v9
	v_add_u32_e32 v39, v36, v39
	v_and_b32_e32 v38, 15, v38
	v_ldexp_f32 v14, v14, v22
	v_cndmask_b32_e32 v14, 0, v14, vcc
	ds_read_b32 v42, v42
	ds_read_b32 v44, v39
	v_mov_b32_e32 v9, v14
	v_sub_f32_e32 v14, v15, v17
	v_mul_f32_e32 v15, 0x3fb8aa3b, v14
	v_fma_f32 v22, v14, s79, -v15
	v_rndne_f32_e32 v23, v15
	v_fmac_f32_e32 v22, 0x32a5705f, v14
	v_sub_f32_e32 v15, v15, v23
	v_add_f32_e32 v15, v15, v22
	v_exp_f32_e32 v15, v15
	v_cvt_i32_f32_e32 v22, v23
	v_cmp_ngt_f32_e32 vcc, s80, v14
	v_add_f32_e32 v12, v12, v9
	v_lshl_add_u32 v38, v38, 2, v36
	v_ldexp_f32 v15, v15, v22
	v_cndmask_b32_e32 v15, 0, v15, vcc
	ds_read_b32 v45, v38 offset:64
	s_nop 0
	v_mov_b32_e32 v14, v15
	v_sub_f32_e32 v15, v20, v17
	v_mul_f32_e32 v20, 0x3fb8aa3b, v15
	v_fma_f32 v22, v15, s79, -v20
	v_rndne_f32_e32 v23, v20
	v_fmac_f32_e32 v22, 0x32a5705f, v15
	v_sub_f32_e32 v20, v20, v23
	v_add_f32_e32 v20, v20, v22
	v_exp_f32_e32 v20, v20
	v_cvt_i32_f32_e32 v22, v23
	v_cmp_ngt_f32_e32 vcc, s80, v15
	v_add_f32_e32 v12, v12, v14
	v_ldexp_f32 v20, v20, v22
	v_cndmask_b32_e32 v20, 0, v20, vcc
	s_nop 1
	v_mov_b32_e32 v15, v20
	v_add_f32_e32 v20, v12, v15
	v_sub_f32_e32 v12, v21, v17
	v_mul_f32_e32 v21, 0x3fb8aa3b, v12
	v_fma_f32 v22, v12, s79, -v21
	v_rndne_f32_e32 v23, v21
	v_fmac_f32_e32 v22, 0x32a5705f, v12
	v_sub_f32_e32 v21, v21, v23
	v_add_f32_e32 v21, v21, v22
	v_exp_f32_e32 v21, v21
	v_cvt_i32_f32_e32 v22, v23
	v_cmp_ngt_f32_e32 vcc, s80, v12
	v_sub_f32_e32 v17, v18, v17
	v_mul_f32_e32 v18, 0x3fb8aa3b, v17
	v_ldexp_f32 v21, v21, v22
	v_cndmask_b32_e32 v21, 0, v21, vcc
	s_nop 1
	v_mov_b32_e32 v12, v21
	v_mul_f32_e32 v21, 0x3fb8aa3b, v13
	v_fma_f32 v22, v13, s79, -v21
	v_rndne_f32_e32 v23, v21
	v_fmac_f32_e32 v22, 0x32a5705f, v13
	v_sub_f32_e32 v21, v21, v23
	v_add_f32_e32 v21, v21, v22
	v_exp_f32_e32 v21, v21
	v_cvt_i32_f32_e32 v22, v23
	v_cmp_ngt_f32_e32 vcc, s80, v13
	v_add_f32_e32 v20, v20, v12
	v_ldexp_f32 v21, v21, v22
	v_cndmask_b32_e32 v21, 0, v21, vcc
	s_nop 1
	v_mov_b32_e32 v13, v21
	v_mul_f32_e32 v21, 0x3fb8aa3b, v16
	v_fma_f32 v22, v16, s79, -v21
	v_rndne_f32_e32 v23, v21
	v_fmac_f32_e32 v22, 0x32a5705f, v16
	v_sub_f32_e32 v21, v21, v23
	v_add_f32_e32 v21, v21, v22
	v_exp_f32_e32 v21, v21
	v_cvt_i32_f32_e32 v22, v23
	v_cmp_ngt_f32_e32 vcc, s80, v16
	v_add_f32_e32 v20, v20, v13
	v_ldexp_f32 v21, v21, v22
	v_cndmask_b32_e32 v21, 0, v21, vcc
	v_rndne_f32_e32 v22, v18
	s_nop 0
	v_mov_b32_e32 v16, v21
	v_fma_f32 v21, v17, s79, -v18
	v_fmac_f32_e32 v21, 0x32a5705f, v17
	v_sub_f32_e32 v18, v18, v22
	v_add_f32_e32 v18, v18, v21
	v_exp_f32_e32 v18, v18
	v_cvt_i32_f32_e32 v21, v22
	v_cmp_ngt_f32_e32 vcc, s80, v17
	v_add_f32_e32 v20, v20, v16
	v_ldexp_f32 v18, v18, v21
	v_cndmask_b32_e32 v18, 0, v18, vcc
	s_nop 1
	v_mov_b32_e32 v17, v18
	v_add_f32_e32 v18, v20, v17
	v_div_scale_f32 v20, s[10:11], v18, v18, 1.0
	v_rcp_f32_e32 v21, v20
	s_nop 0
	v_fma_f32 v22, -v20, v21, 1.0
	v_fmac_f32_e32 v21, v22, v21
	v_div_scale_f32 v22, vcc, 1.0, v18, 1.0
	v_mul_f32_e32 v23, v22, v21
	v_fma_f32 v35, -v20, v23, v22
	v_fmac_f32_e32 v23, v35, v21
	v_fma_f32 v20, -v20, v23, v22
	v_div_fmas_f32 v20, v20, v21, v23
	v_ashrrev_i32_e32 v35, 31, v34
	v_div_fixup_f32 v18, v20, v18, 1.0
	v_lshlrev_b64 v[20:21], 9, v[34:35]
	v_lshrrev_b32_e32 v34, 2, v41
	v_and_b32_e32 v35, 15, v41
	v_lshrrev_b32_e32 v41, 2, v40
	v_and_b32_e32 v41, 60, v41
	v_add_u32_e32 v41, v36, v41
	v_and_b32_e32 v34, 60, v34
	ds_read_b32 v41, v41
	v_add_u32_e32 v34, v36, v34
	v_and_b32_e32 v40, 15, v40
	ds_read_b32 v34, v34
	v_lshl_add_u32 v35, v35, 2, v36
	v_lshl_add_u32 v40, v40, 2, v36
	ds_read_b32 v35, v35 offset:64
	ds_read_b32 v40, v40 offset:64
	s_waitcnt lgkmcnt(3)
	v_lshlrev_b32_e32 v39, 7, v41
	s_waitcnt lgkmcnt(2)
	v_lshlrev_b32_e32 v34, 7, v34
	v_and_b32_e32 v39, 0x3f80, v39
	s_waitcnt lgkmcnt(1)
	v_and_b32_e32 v35, 0x7f, v35
	s_waitcnt lgkmcnt(0)
	v_and_b32_e32 v38, 0x7f, v40
	v_and_b32_e32 v34, 0x3f80, v34
	v_lshlrev_b32_e32 v40, 7, v44
	v_lshlrev_b32_e32 v41, 7, v42
	v_or_b32_e32 v39, v39, v38
	v_or_b32_e32 v38, v34, v35
	v_and_b32_e32 v34, 0x7f, v45
	v_and_b32_e32 v35, 0x7f, v43
	v_and_b32_e32 v40, 0x3f80, v40
	v_and_b32_e32 v42, 0x3f80, v41
	v_lshl_add_u64 v[22:23], s[0:1], 0, v[20:21]
	v_or_b32_e32 v41, v40, v34
	v_or_b32_e32 v40, v42, v35
	global_store_dwordx4 v[22:23], v[38:41], off
	v_lshl_add_u64 v[20:21], s[14:15], 0, v[20:21]
	v_pk_mul_f32 v[4:5], v[4:5], v[18:19] op_sel_hi:[1,0]
	v_pk_mul_f32 v[40:41], v[6:7], v[18:19] op_sel_hi:[1,0]
	v_pk_mul_f32 v[38:39], v[2:3], v[18:19] op_sel_hi:[1,0]
	v_lshrrev_b32_e32 v2, 2, v37
	v_lshrrev_b32_e32 v6, 2, v33
	v_and_b32_e32 v7, 15, v33
	v_lshrrev_b32_e32 v33, 2, v32
	v_and_b32_e32 v32, 15, v32
	v_and_b32_e32 v2, 60, v2
	v_and_b32_e32 v3, 15, v37
	v_and_b32_e32 v6, 60, v6
	v_lshl_add_u32 v32, v32, 2, v36
	v_add_u32_e32 v2, v36, v2
	v_lshl_add_u32 v3, v3, 2, v36
	v_add_u32_e32 v6, v36, v6
	ds_read_b32 v35, v32 offset:64
	v_lshrrev_b32_e32 v32, 2, v31
	ds_read_b32 v2, v2
	ds_read_b32 v3, v3 offset:64
	ds_read_b32 v6, v6
	v_lshl_add_u32 v7, v7, 2, v36
	v_and_b32_e32 v33, 60, v33
	v_and_b32_e32 v32, 60, v32
	ds_read_b32 v7, v7 offset:64
	v_add_u32_e32 v33, v36, v33
	v_add_u32_e32 v32, v36, v32
	v_and_b32_e32 v31, 15, v31
	ds_read_b32 v34, v33
	ds_read_b32 v37, v32
	v_lshl_add_u32 v31, v31, 2, v36
	ds_read_b32 v31, v31 offset:64
	s_waitcnt lgkmcnt(4)
	v_lshlrev_b32_e32 v6, 7, v6
	s_waitcnt lgkmcnt(3)
	v_and_b32_e32 v7, 0x7f, v7
	v_lshlrev_b32_e32 v2, 7, v2
	v_and_b32_e32 v6, 0x3f80, v6
	v_and_b32_e32 v3, 0x7f, v3
	v_and_b32_e32 v2, 0x3f80, v2
	v_or_b32_e32 v33, v6, v7
	s_waitcnt lgkmcnt(1)
	v_lshlrev_b32_e32 v6, 7, v37
	v_lshlrev_b32_e32 v7, 7, v34
	v_or_b32_e32 v32, v2, v3
	s_waitcnt lgkmcnt(0)
	v_and_b32_e32 v2, 0x7f, v31
	v_and_b32_e32 v3, 0x7f, v35
	v_and_b32_e32 v6, 0x3f80, v6
	v_and_b32_e32 v7, 0x3f80, v7
	v_or_b32_e32 v35, v6, v2
	v_or_b32_e32 v34, v7, v3
	v_pk_mul_f32 v[6:7], v[10:11], v[18:19] op_sel_hi:[1,0]
	global_store_dwordx4 v[20:21], v[4:7], off offset:16
	v_lshrrev_b32_e32 v2, 2, v30
	v_and_b32_e32 v2, 60, v2
	v_lshrrev_b32_e32 v4, 2, v29
	v_and_b32_e32 v3, 15, v30
	v_and_b32_e32 v4, 60, v4
	v_add_u32_e32 v2, v36, v2
	v_lshl_add_u32 v3, v3, 2, v36
	v_add_u32_e32 v4, v36, v4
	v_and_b32_e32 v5, 15, v29
	v_lshrrev_b32_e32 v6, 2, v28
	v_lshrrev_b32_e32 v10, 2, v27
	ds_read_b32 v2, v2
	ds_read_b32 v3, v3 offset:64
	ds_read_b32 v4, v4
	v_lshl_add_u32 v5, v5, 2, v36
	v_and_b32_e32 v6, 60, v6
	v_and_b32_e32 v7, 15, v28
	v_and_b32_e32 v10, 60, v10
	ds_read_b32 v5, v5 offset:64
	v_add_u32_e32 v6, v36, v6
	v_lshl_add_u32 v7, v7, 2, v36
	v_add_u32_e32 v10, v36, v10
	v_and_b32_e32 v11, 15, v27
	ds_read_b32 v6, v6
	ds_read_b32 v7, v7 offset:64
	ds_read_b32 v10, v10
	v_lshl_add_u32 v11, v11, 2, v36
	ds_read_b32 v11, v11 offset:64
	s_waitcnt lgkmcnt(6)
	v_and_b32_e32 v27, 0x7f, v3
	s_waitcnt lgkmcnt(5)
	v_lshlrev_b32_e32 v3, 7, v4
	s_waitcnt lgkmcnt(4)
	v_and_b32_e32 v5, 0x7f, v5
	v_and_b32_e32 v3, 0x3f80, v3
	v_lshlrev_b32_e32 v2, 7, v2
	v_or_b32_e32 v3, v3, v5
	s_waitcnt lgkmcnt(1)
	v_lshlrev_b32_e32 v5, 7, v10
	v_lshlrev_b32_e32 v6, 7, v6
	v_and_b32_e32 v2, 0x3f80, v2
	s_waitcnt lgkmcnt(0)
	v_and_b32_e32 v4, 0x7f, v11
	v_and_b32_e32 v7, 0x7f, v7
	v_and_b32_e32 v5, 0x3f80, v5
	v_and_b32_e32 v6, 0x3f80, v6
	v_or_b32_e32 v2, v2, v27
	v_or_b32_e32 v5, v5, v4
	v_or_b32_e32 v4, v6, v7
	global_store_dwordx4 v[22:23], v[2:5], off offset:32
	v_lshrrev_b32_e32 v6, 2, v24
	v_and_b32_e32 v6, 60, v6
	v_pk_mul_f32 v[4:5], v[14:15], v[18:19] op_sel_hi:[1,0]
	v_pk_mul_f32 v[2:3], v[8:9], v[18:19] op_sel_hi:[1,0]
	global_store_dwordx4 v[20:21], v[2:5], off offset:32
	v_lshrrev_b32_e32 v8, 2, v19
	v_and_b32_e32 v7, 15, v24
	v_lshrrev_b32_e32 v2, 2, v26
	v_lshrrev_b32_e32 v4, 2, v25
	v_and_b32_e32 v2, 60, v2
	v_and_b32_e32 v3, 15, v26
	v_and_b32_e32 v4, 60, v4
	v_add_u32_e32 v2, v36, v2
	v_lshl_add_u32 v3, v3, 2, v36
	v_add_u32_e32 v4, v36, v4
	v_and_b32_e32 v5, 15, v25
	ds_read_b32 v2, v2
	ds_read_b32 v3, v3 offset:64
	ds_read_b32 v4, v4
	v_lshl_add_u32 v5, v5, 2, v36
	v_and_b32_e32 v8, 60, v8
	ds_read_b32 v5, v5 offset:64
	v_add_u32_e32 v6, v36, v6
	v_lshl_add_u32 v7, v7, 2, v36
	v_add_u32_e32 v8, v36, v8
	v_and_b32_e32 v9, 15, v19
	ds_read_b32 v6, v6
	ds_read_b32 v7, v7 offset:64
	ds_read_b32 v8, v8
	v_lshl_add_u32 v9, v9, 2, v36
	ds_read_b32 v9, v9 offset:64
	s_waitcnt lgkmcnt(6)
	v_and_b32_e32 v10, 0x7f, v3
	s_waitcnt lgkmcnt(5)
	v_lshlrev_b32_e32 v3, 7, v4
	s_waitcnt lgkmcnt(4)
	v_and_b32_e32 v5, 0x7f, v5
	v_and_b32_e32 v3, 0x3f80, v3
	v_lshlrev_b32_e32 v2, 7, v2
	v_or_b32_e32 v3, v3, v5
	s_waitcnt lgkmcnt(1)
	v_lshlrev_b32_e32 v5, 7, v8
	v_lshlrev_b32_e32 v6, 7, v6
	v_and_b32_e32 v2, 0x3f80, v2
	s_waitcnt lgkmcnt(0)
	v_and_b32_e32 v4, 0x7f, v9
	v_and_b32_e32 v7, 0x7f, v7
	v_and_b32_e32 v5, 0x3f80, v5
	v_and_b32_e32 v6, 0x3f80, v6
	v_or_b32_e32 v2, v2, v10
	v_or_b32_e32 v5, v5, v4
	v_or_b32_e32 v4, v6, v7
	global_store_dwordx4 v[22:23], v[2:5], off offset:48
	global_store_dwordx4 v[20:21], v[38:41], off
	global_store_dwordx4 v[22:23], v[32:35], off offset:16
	v_pk_mul_f32 v[4:5], v[16:17], v[18:19] op_sel_hi:[1,0]
	v_pk_mul_f32 v[2:3], v[12:13], v[18:19] op_sel_hi:[1,0]
	global_store_dwordx4 v[20:21], v[2:5], off offset:48
	s_branch .LBB0_21
